# att in-proj epilogue ssq loads hoisted (gate and q/k paths); out-proj epilogue: next-layer norm weights loaded once instead of per row block, no waits on the stores in between
# speedup vs baseline: 1.0283x; 1.0032x over previous
.LBB0_137:
	s_add_i32 s2, s21, s79
	v_or_b32_e32 v150, s2, v166
	v_or_b32_e32 v156, 16, v150
	v_or_b32_e32 v154, 32, v150
	v_or_b32_e32 v152, 48, v150
	s_cmp_eq_u32 s3, 2
	v_ashrrev_i32_e32 v151, 31, v150
	v_ashrrev_i32_e32 v157, 31, v156
	v_ashrrev_i32_e32 v155, 31, v154
	v_ashrrev_i32_e32 v153, 31, v152
	s_cbranch_scc1 .LBB0_139
	v_lshl_add_u64 v[160:161], v[150:151], 2, s[12:13]
	global_load_dword v0, v[160:161], off
	global_load_dword v229, v[160:161], off offset:64
	global_load_dword v230, v[160:161], off offset:128
	global_load_dword v231, v[160:161], off offset:192
	global_load_dword v232, v[160:161], off offset:512
	global_load_dword v233, v[160:161], off offset:576
	global_load_dword v234, v[160:161], off offset:640
	global_load_dword v235, v[160:161], off offset:704
	v_ashrrev_i32_e32 v147, 31, v146
	s_mov_b64 s[0:1], 0x200000
	s_waitcnt vmcnt(0)
	v_fmamk_f32 v0, v0, 0x3a000000, v197
	v_cmp_gt_f32_e32 vcc, s81, v0
	v_mul_f32_e32 v130, 0x4b800000, v0
	s_nop 0
	v_cndmask_b32_e32 v0, v0, v130, vcc
	v_rsq_f32_e32 v0, v0
	s_nop 0
	v_mul_f32_e32 v130, 0x45800000, v0
	v_cndmask_b32_e32 v0, v0, v130, vcc
	v_lshlrev_b64 v[130:131], 14, v[150:151]
	v_pk_mul_f32 v[162:163], v[126:127], v[0:1] op_sel_hi:[1,0]
	v_lshl_add_u64 v[132:133], s[10:11], 0, v[130:131]
	v_lshlrev_b64 v[130:131], 1, v[146:147]
	v_mul_f32_e32 v147, 0xbfb8aa3b, v162
	v_exp_f32_e32 v147, v147
	v_lshl_add_u64 v[158:159], v[132:133], 0, v[130:131]
	v_pk_mul_f32 v[132:133], v[128:129], v[0:1] op_sel_hi:[1,0]
	v_add_f32_e32 v147, 1.0, v147
	v_rcp_f32_e32 v147, v147
	s_nop 0
	v_mul_f32_e32 v147, v162, v147
	v_mul_f32_e32 v162, 0xbfb8aa3b, v163
	v_exp_f32_e32 v162, v162
	s_nop 0
	v_add_f32_e32 v162, 1.0, v162
	v_rcp_f32_e32 v162, v162
	s_nop 0
	v_mul_f32_e32 v164, v163, v162
	v_mul_f32_e32 v162, 0xbfb8aa3b, v132
	v_exp_f32_e32 v162, v162
	s_nop 0
	v_add_f32_e32 v162, 1.0, v162
	v_rcp_f32_e32 v162, v162
	s_nop 0
	v_mul_f32_e32 v165, v132, v162
	v_pk_mul_f32 v[162:163], v[122:123], v[0:1] op_sel_hi:[1,0]
	v_mul_f32_e32 v132, 0xbfb8aa3b, v133
	v_mul_f32_e32 v168, 0xbfb8aa3b, v162
	v_exp_f32_e32 v168, v168
	v_exp_f32_e32 v132, v132
	v_add_f32_e32 v168, 1.0, v168
	v_rcp_f32_e32 v168, v168
	v_add_f32_e32 v132, 1.0, v132
	v_rcp_f32_e32 v132, v132
	v_mul_f32_e32 v168, v162, v168
	v_mul_f32_e32 v162, 0xbfb8aa3b, v163
	v_exp_f32_e32 v162, v162
	v_mul_f32_e32 v167, v133, v132
	v_pk_mul_f32 v[132:133], v[124:125], v[0:1] op_sel_hi:[1,0]
	v_add_f32_e32 v162, 1.0, v162
	v_rcp_f32_e32 v162, v162
	s_nop 0
	v_mul_f32_e32 v169, v163, v162
	v_mul_f32_e32 v162, 0xbfb8aa3b, v132
	v_exp_f32_e32 v162, v162
	s_nop 0
	v_add_f32_e32 v162, 1.0, v162
	v_rcp_f32_e32 v162, v162
	s_nop 0
	v_mul_f32_e32 v132, v132, v162
	v_mul_f32_e32 v162, 0xbfb8aa3b, v133
	v_exp_f32_e32 v162, v162
	s_nop 0
	v_add_f32_e32 v162, 1.0, v162
	v_rcp_f32_e32 v162, v162
	s_nop 0
	v_mul_f32_e32 v133, v133, v162
	v_cvt_pk_bf16_f32 v162, v147, v164
	v_cvt_pk_bf16_f32 v163, v165, v167
	v_cvt_pk_bf16_f32 v164, v168, v169
	v_cvt_pk_bf16_f32 v165, v132, v133
	global_store_dwordx4 v[158:159], v[162:165], off
	v_pk_mul_f32 v[132:133], v[120:121], v[0:1] op_sel_hi:[1,0]
	s_nop 0
	v_pk_mul_f32 v[162:163], v[118:119], v[0:1] op_sel_hi:[1,0]
	s_nop 0
	v_mul_f32_e32 v147, 0xbfb8aa3b, v162
	v_exp_f32_e32 v147, v147
	s_nop 0
	v_add_f32_e32 v147, 1.0, v147
	v_rcp_f32_e32 v147, v147
	s_nop 0
	v_mul_f32_e32 v147, v162, v147
	v_mul_f32_e32 v162, 0xbfb8aa3b, v163
	v_exp_f32_e32 v162, v162
	s_nop 0
	v_add_f32_e32 v162, 1.0, v162
	v_rcp_f32_e32 v162, v162
	s_nop 0
	v_mul_f32_e32 v164, v163, v162
	v_mul_f32_e32 v162, 0xbfb8aa3b, v132
	v_exp_f32_e32 v162, v162
	s_nop 0
	v_add_f32_e32 v162, 1.0, v162
	v_rcp_f32_e32 v162, v162
	s_nop 0
	v_mul_f32_e32 v165, v132, v162
	v_mul_f32_e32 v132, 0xbfb8aa3b, v133
	v_exp_f32_e32 v132, v132
	v_pk_mul_f32 v[162:163], v[114:115], v[0:1] op_sel_hi:[1,0]
	v_add_f32_e32 v132, 1.0, v132
	v_rcp_f32_e32 v132, v132
	s_nop 0
	v_mul_f32_e32 v167, v133, v132
	v_pk_mul_f32 v[132:133], v[116:117], v[0:1] op_sel_hi:[1,0]
	v_mul_f32_e32 v0, 0xbfb8aa3b, v162
	v_exp_f32_e32 v0, v0
	s_nop 0
	v_add_f32_e32 v0, 1.0, v0
	v_rcp_f32_e32 v0, v0
	s_nop 0
	v_mul_f32_e32 v0, v162, v0
	v_mul_f32_e32 v162, 0xbfb8aa3b, v163
	v_exp_f32_e32 v162, v162
	s_nop 0
	v_add_f32_e32 v162, 1.0, v162
	v_rcp_f32_e32 v162, v162
	s_nop 0
	v_mul_f32_e32 v168, v163, v162
	v_mul_f32_e32 v162, 0xbfb8aa3b, v132
	v_exp_f32_e32 v162, v162
	s_nop 0
	v_add_f32_e32 v162, 1.0, v162
	v_rcp_f32_e32 v162, v162
	s_nop 0
	v_mul_f32_e32 v132, v132, v162
	v_mul_f32_e32 v162, 0xbfb8aa3b, v133
	v_exp_f32_e32 v162, v162
	s_nop 0
	v_add_f32_e32 v162, 1.0, v162
	v_rcp_f32_e32 v162, v162
	s_nop 0
	v_mul_f32_e32 v133, v133, v162
	v_cvt_pk_bf16_f32 v162, v147, v164
	v_cvt_pk_bf16_f32 v163, v165, v167
	v_cvt_pk_bf16_f32 v164, v0, v168
	v_cvt_pk_bf16_f32 v165, v132, v133
	global_store_dwordx4 v[158:159], v[162:165], off offset:256
	v_lshl_add_u64 v[132:133], v[156:157], 2, s[12:13]
	v_mov_b32_e32 v0, v229
	v_fmamk_f32 v0, v0, 0x3a000000, v197
	v_cmp_gt_f32_e32 vcc, s81, v0
	v_mul_f32_e32 v132, 0x4b800000, v0
	s_nop 0
	v_cndmask_b32_e32 v0, v0, v132, vcc
	v_rsq_f32_e32 v0, v0
	s_nop 0
	v_mul_f32_e32 v132, 0x45800000, v0
	v_cndmask_b32_e32 v0, v0, v132, vcc
	v_pk_mul_f32 v[164:165], v[110:111], v[0:1] op_sel_hi:[1,0]
	v_pk_mul_f32 v[162:163], v[112:113], v[0:1] op_sel_hi:[1,0]
	v_mul_f32_e32 v147, 0xbfb8aa3b, v164
	v_exp_f32_e32 v147, v147
	v_lshlrev_b64 v[132:133], 14, v[156:157]
	v_lshl_add_u64 v[132:133], s[10:11], 0, v[132:133]
	v_lshl_add_u64 v[132:133], v[132:133], 0, v[130:131]
	v_add_f32_e32 v147, 1.0, v147
	v_rcp_f32_e32 v147, v147
	s_nop 0
	v_mul_f32_e32 v147, v164, v147
	v_mul_f32_e32 v164, 0xbfb8aa3b, v165
	v_exp_f32_e32 v164, v164
	s_nop 0
	v_add_f32_e32 v164, 1.0, v164
	v_rcp_f32_e32 v164, v164
	s_nop 0
	v_mul_f32_e32 v167, v165, v164
	v_mul_f32_e32 v164, 0xbfb8aa3b, v162
	v_exp_f32_e32 v164, v164
	s_nop 0
	v_add_f32_e32 v164, 1.0, v164
	v_rcp_f32_e32 v164, v164
	s_nop 0
	v_mul_f32_e32 v168, v162, v164
	v_pk_mul_f32 v[164:165], v[106:107], v[0:1] op_sel_hi:[1,0]
	v_mul_f32_e32 v162, 0xbfb8aa3b, v163
	v_mul_f32_e32 v170, 0xbfb8aa3b, v164
	v_exp_f32_e32 v170, v170
	v_exp_f32_e32 v162, v162
	v_add_f32_e32 v170, 1.0, v170
	v_rcp_f32_e32 v170, v170
	v_add_f32_e32 v162, 1.0, v162
	v_rcp_f32_e32 v162, v162
	v_mul_f32_e32 v164, v164, v170
	v_mul_f32_e32 v170, 0xbfb8aa3b, v165
	v_exp_f32_e32 v170, v170
	v_mul_f32_e32 v169, v163, v162
	v_pk_mul_f32 v[162:163], v[108:109], v[0:1] op_sel_hi:[1,0]
	v_add_f32_e32 v170, 1.0, v170
	v_rcp_f32_e32 v170, v170
	s_nop 0
	v_mul_f32_e32 v165, v165, v170
	v_mul_f32_e32 v170, 0xbfb8aa3b, v162
	v_exp_f32_e32 v170, v170
	s_nop 0
	v_add_f32_e32 v170, 1.0, v170
	v_rcp_f32_e32 v170, v170
	s_nop 0
	v_mul_f32_e32 v170, v162, v170
	v_mul_f32_e32 v162, 0xbfb8aa3b, v163
	v_exp_f32_e32 v162, v162
	s_nop 0
	v_add_f32_e32 v162, 1.0, v162
	v_rcp_f32_e32 v162, v162
	s_nop 0
	v_mul_f32_e32 v171, v163, v162
	v_cvt_pk_bf16_f32 v162, v147, v167
	v_cvt_pk_bf16_f32 v163, v168, v169
	v_cvt_pk_bf16_f32 v164, v164, v165
	v_cvt_pk_bf16_f32 v165, v170, v171
	global_store_dwordx4 v[132:133], v[162:165], off
	s_nop 1
	v_pk_mul_f32 v[164:165], v[102:103], v[0:1] op_sel_hi:[1,0]
	v_pk_mul_f32 v[162:163], v[104:105], v[0:1] op_sel_hi:[1,0]
	v_mul_f32_e32 v147, 0xbfb8aa3b, v164
	v_exp_f32_e32 v147, v147
	s_nop 0
	v_add_f32_e32 v147, 1.0, v147
	v_rcp_f32_e32 v147, v147
	s_nop 0
	v_mul_f32_e32 v147, v164, v147
	v_mul_f32_e32 v164, 0xbfb8aa3b, v165
	v_exp_f32_e32 v164, v164
	s_nop 0
	v_add_f32_e32 v164, 1.0, v164
	v_rcp_f32_e32 v164, v164
	s_nop 0
	v_mul_f32_e32 v167, v165, v164
	v_mul_f32_e32 v164, 0xbfb8aa3b, v162
	v_exp_f32_e32 v164, v164
	s_nop 0
	v_add_f32_e32 v164, 1.0, v164
	v_rcp_f32_e32 v164, v164
	s_nop 0
	v_mul_f32_e32 v168, v162, v164
	v_mul_f32_e32 v162, 0xbfb8aa3b, v163
	v_exp_f32_e32 v162, v162
	v_pk_mul_f32 v[164:165], v[98:99], v[0:1] op_sel_hi:[1,0]
	v_add_f32_e32 v162, 1.0, v162
	v_rcp_f32_e32 v162, v162
	s_nop 0
	v_mul_f32_e32 v169, v163, v162
	v_pk_mul_f32 v[162:163], v[100:101], v[0:1] op_sel_hi:[1,0]
	v_mul_f32_e32 v0, 0xbfb8aa3b, v164
	v_exp_f32_e32 v0, v0
	s_nop 0
	v_add_f32_e32 v0, 1.0, v0
	v_rcp_f32_e32 v0, v0
	s_nop 0
	v_mul_f32_e32 v0, v164, v0
	v_mul_f32_e32 v164, 0xbfb8aa3b, v165
	v_exp_f32_e32 v164, v164
	s_nop 0
	v_add_f32_e32 v164, 1.0, v164
	v_rcp_f32_e32 v164, v164
	s_nop 0
	v_mul_f32_e32 v164, v165, v164
	v_mul_f32_e32 v165, 0xbfb8aa3b, v162
	v_exp_f32_e32 v165, v165
	s_nop 0
	v_add_f32_e32 v165, 1.0, v165
	v_rcp_f32_e32 v165, v165
	s_nop 0
	v_mul_f32_e32 v165, v162, v165
	v_mul_f32_e32 v162, 0xbfb8aa3b, v163
	v_exp_f32_e32 v162, v162
	s_nop 0
	v_add_f32_e32 v162, 1.0, v162
	v_rcp_f32_e32 v162, v162
	s_nop 0
	v_mul_f32_e32 v170, v163, v162
	v_cvt_pk_bf16_f32 v162, v147, v167
	v_cvt_pk_bf16_f32 v163, v168, v169
	v_cvt_pk_bf16_f32 v164, v0, v164
	v_cvt_pk_bf16_f32 v165, v165, v170
	global_store_dwordx4 v[132:133], v[162:165], off offset:256
	v_lshl_add_u64 v[132:133], v[154:155], 2, s[12:13]
	v_mov_b32_e32 v0, v230
	v_fmamk_f32 v0, v0, 0x3a000000, v197
	v_cmp_gt_f32_e32 vcc, s81, v0
	v_mul_f32_e32 v132, 0x4b800000, v0
	s_nop 0
	v_cndmask_b32_e32 v0, v0, v132, vcc
	v_rsq_f32_e32 v0, v0
	s_nop 0
	v_mul_f32_e32 v132, 0x45800000, v0
	v_cndmask_b32_e32 v0, v0, v132, vcc
	v_pk_mul_f32 v[164:165], v[94:95], v[0:1] op_sel_hi:[1,0]
	v_pk_mul_f32 v[162:163], v[96:97], v[0:1] op_sel_hi:[1,0]
	v_mul_f32_e32 v147, 0xbfb8aa3b, v164
	v_exp_f32_e32 v147, v147
	v_lshlrev_b64 v[132:133], 14, v[154:155]
	v_lshl_add_u64 v[132:133], s[10:11], 0, v[132:133]
	v_lshl_add_u64 v[132:133], v[132:133], 0, v[130:131]
	v_add_f32_e32 v147, 1.0, v147
	v_rcp_f32_e32 v147, v147
	s_nop 0
	v_mul_f32_e32 v147, v164, v147
	v_mul_f32_e32 v164, 0xbfb8aa3b, v165
	v_exp_f32_e32 v164, v164
	s_nop 0
	v_add_f32_e32 v164, 1.0, v164
	v_rcp_f32_e32 v164, v164
	s_nop 0
	v_mul_f32_e32 v167, v165, v164
	v_mul_f32_e32 v164, 0xbfb8aa3b, v162
	v_exp_f32_e32 v164, v164
	s_nop 0
	v_add_f32_e32 v164, 1.0, v164
	v_rcp_f32_e32 v164, v164
	s_nop 0
	v_mul_f32_e32 v168, v162, v164
	v_pk_mul_f32 v[164:165], v[90:91], v[0:1] op_sel_hi:[1,0]
	v_mul_f32_e32 v162, 0xbfb8aa3b, v163
	v_mul_f32_e32 v170, 0xbfb8aa3b, v164
	v_exp_f32_e32 v170, v170
	v_exp_f32_e32 v162, v162
	v_add_f32_e32 v170, 1.0, v170
	v_rcp_f32_e32 v170, v170
	v_add_f32_e32 v162, 1.0, v162
	v_rcp_f32_e32 v162, v162
	v_mul_f32_e32 v164, v164, v170
	v_mul_f32_e32 v170, 0xbfb8aa3b, v165
	v_exp_f32_e32 v170, v170
	v_mul_f32_e32 v169, v163, v162
	v_pk_mul_f32 v[162:163], v[92:93], v[0:1] op_sel_hi:[1,0]
	v_add_f32_e32 v170, 1.0, v170
	v_rcp_f32_e32 v170, v170
	s_nop 0
	v_mul_f32_e32 v165, v165, v170
	v_mul_f32_e32 v170, 0xbfb8aa3b, v162
	v_exp_f32_e32 v170, v170
	s_nop 0
	v_add_f32_e32 v170, 1.0, v170
	v_rcp_f32_e32 v170, v170
	s_nop 0
	v_mul_f32_e32 v170, v162, v170
	v_mul_f32_e32 v162, 0xbfb8aa3b, v163
	v_exp_f32_e32 v162, v162
	s_nop 0
	v_add_f32_e32 v162, 1.0, v162
	v_rcp_f32_e32 v162, v162
	s_nop 0
	v_mul_f32_e32 v171, v163, v162
	v_cvt_pk_bf16_f32 v162, v147, v167
	v_cvt_pk_bf16_f32 v163, v168, v169
	v_cvt_pk_bf16_f32 v164, v164, v165
	v_cvt_pk_bf16_f32 v165, v170, v171
	global_store_dwordx4 v[132:133], v[162:165], off
	s_nop 1
	v_pk_mul_f32 v[164:165], v[86:87], v[0:1] op_sel_hi:[1,0]
	v_pk_mul_f32 v[162:163], v[88:89], v[0:1] op_sel_hi:[1,0]
	v_mul_f32_e32 v147, 0xbfb8aa3b, v164
	v_exp_f32_e32 v147, v147
	s_nop 0
	v_add_f32_e32 v147, 1.0, v147
	v_rcp_f32_e32 v147, v147
	s_nop 0
	v_mul_f32_e32 v147, v164, v147
	v_mul_f32_e32 v164, 0xbfb8aa3b, v165
	v_exp_f32_e32 v164, v164
	s_nop 0
	v_add_f32_e32 v164, 1.0, v164
	v_rcp_f32_e32 v164, v164
	s_nop 0
	v_mul_f32_e32 v167, v165, v164
	v_mul_f32_e32 v164, 0xbfb8aa3b, v162
	v_exp_f32_e32 v164, v164
	s_nop 0
	v_add_f32_e32 v164, 1.0, v164
	v_rcp_f32_e32 v164, v164
	s_nop 0
	v_mul_f32_e32 v168, v162, v164
	v_mul_f32_e32 v162, 0xbfb8aa3b, v163
	v_exp_f32_e32 v162, v162
	v_pk_mul_f32 v[164:165], v[82:83], v[0:1] op_sel_hi:[1,0]
	v_add_f32_e32 v162, 1.0, v162
	v_rcp_f32_e32 v162, v162
	s_nop 0
	v_mul_f32_e32 v169, v163, v162
	v_pk_mul_f32 v[162:163], v[84:85], v[0:1] op_sel_hi:[1,0]
	v_mul_f32_e32 v0, 0xbfb8aa3b, v164
	v_exp_f32_e32 v0, v0
	s_nop 0
	v_add_f32_e32 v0, 1.0, v0
	v_rcp_f32_e32 v0, v0
	s_nop 0
	v_mul_f32_e32 v0, v164, v0
	v_mul_f32_e32 v164, 0xbfb8aa3b, v165
	v_exp_f32_e32 v164, v164
	s_nop 0
	v_add_f32_e32 v164, 1.0, v164
	v_rcp_f32_e32 v164, v164
	s_nop 0
	v_mul_f32_e32 v164, v165, v164
	v_mul_f32_e32 v165, 0xbfb8aa3b, v162
	v_exp_f32_e32 v165, v165
	s_nop 0
	v_add_f32_e32 v165, 1.0, v165
	v_rcp_f32_e32 v165, v165
	s_nop 0
	v_mul_f32_e32 v165, v162, v165
	v_mul_f32_e32 v162, 0xbfb8aa3b, v163
	v_exp_f32_e32 v162, v162
	s_nop 0
	v_add_f32_e32 v162, 1.0, v162
	v_rcp_f32_e32 v162, v162
	s_nop 0
	v_mul_f32_e32 v170, v163, v162
	v_cvt_pk_bf16_f32 v162, v147, v167
	v_cvt_pk_bf16_f32 v163, v168, v169
	v_cvt_pk_bf16_f32 v164, v0, v164
	v_cvt_pk_bf16_f32 v165, v165, v170
	global_store_dwordx4 v[132:133], v[162:165], off offset:256
	v_lshl_add_u64 v[132:133], v[152:153], 2, s[12:13]
	v_mov_b32_e32 v0, v231
	v_fmamk_f32 v0, v0, 0x3a000000, v197
	v_cmp_gt_f32_e32 vcc, s81, v0
	v_mul_f32_e32 v132, 0x4b800000, v0
	s_nop 0
	v_cndmask_b32_e32 v0, v0, v132, vcc
	v_rsq_f32_e32 v0, v0
	s_nop 0
	v_mul_f32_e32 v132, 0x45800000, v0
	v_cndmask_b32_e32 v0, v0, v132, vcc
	v_pk_mul_f32 v[162:163], v[78:79], v[0:1] op_sel_hi:[1,0]
	v_lshlrev_b64 v[132:133], 14, v[152:153]
	v_mul_f32_e32 v147, 0xbfb8aa3b, v162
	v_exp_f32_e32 v147, v147
	v_lshl_add_u64 v[132:133], s[10:11], 0, v[132:133]
	v_lshl_add_u64 v[130:131], v[132:133], 0, v[130:131]
	v_pk_mul_f32 v[132:133], v[80:81], v[0:1] op_sel_hi:[1,0]
	v_add_f32_e32 v147, 1.0, v147
	v_rcp_f32_e32 v147, v147
	s_nop 0
	v_mul_f32_e32 v147, v162, v147
	v_mul_f32_e32 v162, 0xbfb8aa3b, v163
	v_exp_f32_e32 v162, v162
	s_nop 0
	v_add_f32_e32 v162, 1.0, v162
	v_rcp_f32_e32 v162, v162
	s_nop 0
	v_mul_f32_e32 v164, v163, v162
	v_mul_f32_e32 v162, 0xbfb8aa3b, v132
	v_exp_f32_e32 v162, v162
	s_nop 0
	v_add_f32_e32 v162, 1.0, v162
	v_rcp_f32_e32 v162, v162
	s_nop 0
	v_mul_f32_e32 v165, v132, v162
	v_pk_mul_f32 v[162:163], v[74:75], v[0:1] op_sel_hi:[1,0]
	v_mul_f32_e32 v132, 0xbfb8aa3b, v133
	v_mul_f32_e32 v168, 0xbfb8aa3b, v162
	v_exp_f32_e32 v168, v168
	v_exp_f32_e32 v132, v132
	v_add_f32_e32 v168, 1.0, v168
	v_rcp_f32_e32 v168, v168
	v_add_f32_e32 v132, 1.0, v132
	v_rcp_f32_e32 v132, v132
	v_mul_f32_e32 v168, v162, v168
	v_mul_f32_e32 v162, 0xbfb8aa3b, v163
	v_exp_f32_e32 v162, v162
	v_mul_f32_e32 v167, v133, v132
	v_pk_mul_f32 v[132:133], v[76:77], v[0:1] op_sel_hi:[1,0]
	v_add_f32_e32 v162, 1.0, v162
	v_rcp_f32_e32 v162, v162
	s_nop 0
	v_mul_f32_e32 v169, v163, v162
	v_mul_f32_e32 v162, 0xbfb8aa3b, v132
	v_exp_f32_e32 v162, v162
	s_nop 0
	v_add_f32_e32 v162, 1.0, v162
	v_rcp_f32_e32 v162, v162
	s_nop 0
	v_mul_f32_e32 v132, v132, v162
	v_mul_f32_e32 v162, 0xbfb8aa3b, v133
	v_exp_f32_e32 v162, v162
	s_nop 0
	v_add_f32_e32 v162, 1.0, v162
	v_rcp_f32_e32 v162, v162
	s_nop 0
	v_mul_f32_e32 v133, v133, v162
	v_cvt_pk_bf16_f32 v162, v147, v164
	v_cvt_pk_bf16_f32 v163, v165, v167
	v_cvt_pk_bf16_f32 v164, v168, v169
	v_cvt_pk_bf16_f32 v165, v132, v133
	global_store_dwordx4 v[130:131], v[162:165], off
	v_pk_mul_f32 v[132:133], v[72:73], v[0:1] op_sel_hi:[1,0]
	s_nop 0
	v_pk_mul_f32 v[162:163], v[70:71], v[0:1] op_sel_hi:[1,0]
	s_nop 0
	v_mul_f32_e32 v147, 0xbfb8aa3b, v162
	v_exp_f32_e32 v147, v147
	s_nop 0
	v_add_f32_e32 v147, 1.0, v147
	v_rcp_f32_e32 v147, v147
	s_nop 0
	v_mul_f32_e32 v147, v162, v147
	v_mul_f32_e32 v162, 0xbfb8aa3b, v163
	v_exp_f32_e32 v162, v162
	s_nop 0
	v_add_f32_e32 v162, 1.0, v162
	v_rcp_f32_e32 v162, v162
	s_nop 0
	v_mul_f32_e32 v164, v163, v162
	v_mul_f32_e32 v162, 0xbfb8aa3b, v132
	v_exp_f32_e32 v162, v162
	s_nop 0
	v_add_f32_e32 v162, 1.0, v162
	v_rcp_f32_e32 v162, v162
	s_nop 0
	v_mul_f32_e32 v165, v132, v162
	v_mul_f32_e32 v132, 0xbfb8aa3b, v133
	v_exp_f32_e32 v132, v132
	v_pk_mul_f32 v[162:163], v[66:67], v[0:1] op_sel_hi:[1,0]
	v_add_f32_e32 v132, 1.0, v132
	v_rcp_f32_e32 v132, v132
	s_nop 0
	v_mul_f32_e32 v167, v133, v132
	v_pk_mul_f32 v[132:133], v[68:69], v[0:1] op_sel_hi:[1,0]
	v_mul_f32_e32 v0, 0xbfb8aa3b, v162
	v_exp_f32_e32 v0, v0
	s_nop 0
	v_add_f32_e32 v0, 1.0, v0
	v_rcp_f32_e32 v0, v0
	s_nop 0
	v_mul_f32_e32 v0, v162, v0
	v_mul_f32_e32 v162, 0xbfb8aa3b, v163
	v_exp_f32_e32 v162, v162
	s_nop 0
	v_add_f32_e32 v162, 1.0, v162
	v_rcp_f32_e32 v162, v162
	s_nop 0
	v_mul_f32_e32 v168, v163, v162
	v_mul_f32_e32 v162, 0xbfb8aa3b, v132
	v_exp_f32_e32 v162, v162
	s_nop 0
	v_add_f32_e32 v162, 1.0, v162
	v_rcp_f32_e32 v162, v162
	s_nop 0
	v_mul_f32_e32 v132, v132, v162
	v_mul_f32_e32 v162, 0xbfb8aa3b, v133
	v_exp_f32_e32 v162, v162
	s_nop 0
	v_add_f32_e32 v162, 1.0, v162
	v_rcp_f32_e32 v162, v162
	s_nop 0
	v_mul_f32_e32 v133, v133, v162
	v_cvt_pk_bf16_f32 v162, v147, v164
	v_cvt_pk_bf16_f32 v163, v165, v167
	v_cvt_pk_bf16_f32 v164, v0, v168
	v_cvt_pk_bf16_f32 v165, v132, v133
	global_store_dwordx4 v[130:131], v[162:165], off offset:256
	v_mov_b32_e32 v0, v232
	v_fmamk_f32 v0, v0, 0x3a000000, v197
	v_cmp_gt_f32_e32 vcc, s81, v0
	v_mul_f32_e32 v130, 0x4b800000, v0
	s_nop 0
	v_cndmask_b32_e32 v0, v0, v130, vcc
	v_rsq_f32_e32 v0, v0
	s_nop 0
	v_mul_f32_e32 v130, 0x45800000, v0
	v_cndmask_b32_e32 v0, v0, v130, vcc
	v_pk_mul_f32 v[162:163], v[62:63], v[0:1] op_sel_hi:[1,0]
	v_pk_mul_f32 v[132:133], v[64:65], v[0:1] op_sel_hi:[1,0]
	v_mul_f32_e32 v147, 0xbfb8aa3b, v162
	v_exp_f32_e32 v147, v147
	v_lshl_add_u64 v[130:131], v[158:159], 0, s[0:1]
	s_mov_b32 s0, 0x200000
	v_add_f32_e32 v147, 1.0, v147
	v_rcp_f32_e32 v147, v147
	s_nop 0
	v_mul_f32_e32 v147, v162, v147
	v_mul_f32_e32 v162, 0xbfb8aa3b, v163
	v_exp_f32_e32 v162, v162
	s_nop 0
	v_add_f32_e32 v162, 1.0, v162
	v_rcp_f32_e32 v162, v162
	s_nop 0
	v_mul_f32_e32 v164, v163, v162
	v_mul_f32_e32 v162, 0xbfb8aa3b, v132
	v_exp_f32_e32 v162, v162
	s_nop 0
	v_add_f32_e32 v162, 1.0, v162
	v_rcp_f32_e32 v162, v162
	s_nop 0
	v_mul_f32_e32 v165, v132, v162
	v_pk_mul_f32 v[162:163], v[58:59], v[0:1] op_sel_hi:[1,0]
	v_mul_f32_e32 v132, 0xbfb8aa3b, v133
	v_mul_f32_e32 v168, 0xbfb8aa3b, v162
	v_exp_f32_e32 v168, v168
	v_exp_f32_e32 v132, v132
	v_add_f32_e32 v168, 1.0, v168
	v_rcp_f32_e32 v168, v168
	v_add_f32_e32 v132, 1.0, v132
	v_rcp_f32_e32 v132, v132
	v_mul_f32_e32 v168, v162, v168
	v_mul_f32_e32 v162, 0xbfb8aa3b, v163
	v_exp_f32_e32 v162, v162
	v_mul_f32_e32 v167, v133, v132
	v_pk_mul_f32 v[132:133], v[60:61], v[0:1] op_sel_hi:[1,0]
	v_add_f32_e32 v162, 1.0, v162
	v_rcp_f32_e32 v162, v162
	s_nop 0
	v_mul_f32_e32 v169, v163, v162
	v_mul_f32_e32 v162, 0xbfb8aa3b, v132
	v_exp_f32_e32 v162, v162
	s_nop 0
	v_add_f32_e32 v162, 1.0, v162
	v_rcp_f32_e32 v162, v162
	s_nop 0
	v_mul_f32_e32 v132, v132, v162
	v_mul_f32_e32 v162, 0xbfb8aa3b, v133
	v_exp_f32_e32 v162, v162
	s_nop 0
	v_add_f32_e32 v162, 1.0, v162
	v_rcp_f32_e32 v162, v162
	s_nop 0
	v_mul_f32_e32 v133, v133, v162
	v_cvt_pk_bf16_f32 v162, v147, v164
	v_cvt_pk_bf16_f32 v163, v165, v167
	v_cvt_pk_bf16_f32 v164, v168, v169
	v_cvt_pk_bf16_f32 v165, v132, v133
	v_add_co_u32_e32 v132, vcc, s0, v158
	s_mov_b64 s[0:1], 0x240000
	s_nop 0
	v_addc_co_u32_e32 v133, vcc, 0, v159, vcc
	global_store_dwordx4 v[132:133], v[162:165], off
	v_pk_mul_f32 v[132:133], v[56:57], v[0:1] op_sel_hi:[1,0]
	s_nop 0
	v_pk_mul_f32 v[162:163], v[54:55], v[0:1] op_sel_hi:[1,0]
	s_nop 0
	v_mul_f32_e32 v147, 0xbfb8aa3b, v162
	v_exp_f32_e32 v147, v147
	s_nop 0
	v_add_f32_e32 v147, 1.0, v147
	v_rcp_f32_e32 v147, v147
	s_nop 0
	v_mul_f32_e32 v147, v162, v147
	v_mul_f32_e32 v162, 0xbfb8aa3b, v163
	v_exp_f32_e32 v162, v162
	s_nop 0
	v_add_f32_e32 v162, 1.0, v162
	v_rcp_f32_e32 v162, v162
	s_nop 0
	v_mul_f32_e32 v164, v163, v162
	v_mul_f32_e32 v162, 0xbfb8aa3b, v132
	v_exp_f32_e32 v162, v162
	s_nop 0
	v_add_f32_e32 v162, 1.0, v162
	v_rcp_f32_e32 v162, v162
	s_nop 0
	v_mul_f32_e32 v165, v132, v162
	v_mul_f32_e32 v132, 0xbfb8aa3b, v133
	v_exp_f32_e32 v132, v132
	v_pk_mul_f32 v[162:163], v[50:51], v[0:1] op_sel_hi:[1,0]
	v_add_f32_e32 v132, 1.0, v132
	v_rcp_f32_e32 v132, v132
	s_nop 0
	v_mul_f32_e32 v167, v133, v132
	v_pk_mul_f32 v[132:133], v[52:53], v[0:1] op_sel_hi:[1,0]
	v_mul_f32_e32 v0, 0xbfb8aa3b, v162
	v_exp_f32_e32 v0, v0
	s_nop 0
	v_add_f32_e32 v0, 1.0, v0
	v_rcp_f32_e32 v0, v0
	s_nop 0
	v_mul_f32_e32 v0, v162, v0
	v_mul_f32_e32 v162, 0xbfb8aa3b, v163
	v_exp_f32_e32 v162, v162
	s_nop 0
	v_add_f32_e32 v162, 1.0, v162
	v_rcp_f32_e32 v162, v162
	s_nop 0
	v_mul_f32_e32 v168, v163, v162
	v_mul_f32_e32 v162, 0xbfb8aa3b, v132
	v_exp_f32_e32 v162, v162
	s_nop 0
	v_add_f32_e32 v162, 1.0, v162
	v_rcp_f32_e32 v162, v162
	s_nop 0
	v_mul_f32_e32 v132, v132, v162
	v_mul_f32_e32 v162, 0xbfb8aa3b, v133
	v_exp_f32_e32 v162, v162
	s_nop 0
	v_add_f32_e32 v162, 1.0, v162
	v_rcp_f32_e32 v162, v162
	s_nop 0
	v_mul_f32_e32 v133, v133, v162
	v_cvt_pk_bf16_f32 v162, v147, v164
	v_cvt_pk_bf16_f32 v163, v165, v167
	v_cvt_pk_bf16_f32 v164, v0, v168
	v_cvt_pk_bf16_f32 v165, v132, v133
	global_store_dwordx4 v[130:131], v[162:165], off offset:256
	v_mov_b32_e32 v0, v233
	v_fmamk_f32 v0, v0, 0x3a000000, v197
	v_cmp_gt_f32_e32 vcc, s81, v0
	v_mul_f32_e32 v130, 0x4b800000, v0
	v_lshl_add_u64 v[162:163], v[158:159], 0, s[0:1]
	v_cndmask_b32_e32 v0, v0, v130, vcc
	v_rsq_f32_e32 v0, v0
	s_mov_b32 s0, 0x240000
	v_mul_f32_e32 v130, 0x45800000, v0
	v_cndmask_b32_e32 v0, v0, v130, vcc
	v_pk_mul_f32 v[132:133], v[46:47], v[0:1] op_sel_hi:[1,0]
	v_pk_mul_f32 v[130:131], v[48:49], v[0:1] op_sel_hi:[1,0]
	v_mul_f32_e32 v147, 0xbfb8aa3b, v132
	v_exp_f32_e32 v147, v147
	s_nop 0
	v_add_f32_e32 v147, 1.0, v147
	v_rcp_f32_e32 v147, v147
	s_nop 0
	v_mul_f32_e32 v147, v132, v147
	v_mul_f32_e32 v132, 0xbfb8aa3b, v133
	v_exp_f32_e32 v132, v132
	s_nop 0
	v_add_f32_e32 v132, 1.0, v132
	v_rcp_f32_e32 v132, v132
	s_nop 0
	v_mul_f32_e32 v164, v133, v132
	v_mul_f32_e32 v132, 0xbfb8aa3b, v130
	v_exp_f32_e32 v132, v132
	s_nop 0
	v_add_f32_e32 v132, 1.0, v132
	v_rcp_f32_e32 v132, v132
	s_nop 0
	v_mul_f32_e32 v165, v130, v132
	v_pk_mul_f32 v[132:133], v[42:43], v[0:1] op_sel_hi:[1,0]
	v_mul_f32_e32 v130, 0xbfb8aa3b, v131
	v_mul_f32_e32 v168, 0xbfb8aa3b, v132
	v_exp_f32_e32 v168, v168
	v_exp_f32_e32 v130, v130
	v_add_f32_e32 v168, 1.0, v168
	v_rcp_f32_e32 v168, v168
	v_add_f32_e32 v130, 1.0, v130
	v_rcp_f32_e32 v130, v130
	v_mul_f32_e32 v132, v132, v168
	v_mul_f32_e32 v168, 0xbfb8aa3b, v133
	v_exp_f32_e32 v168, v168
	v_mul_f32_e32 v167, v131, v130
	v_pk_mul_f32 v[130:131], v[44:45], v[0:1] op_sel_hi:[1,0]
	v_add_f32_e32 v168, 1.0, v168
	v_rcp_f32_e32 v168, v168
	s_nop 0
	v_mul_f32_e32 v133, v133, v168
	v_mul_f32_e32 v168, 0xbfb8aa3b, v130
	v_exp_f32_e32 v168, v168
	s_nop 0
	v_add_f32_e32 v168, 1.0, v168
	v_rcp_f32_e32 v168, v168
	s_nop 0
	v_mul_f32_e32 v168, v130, v168
	v_mul_f32_e32 v130, 0xbfb8aa3b, v131
	v_exp_f32_e32 v130, v130
	s_nop 0
	v_add_f32_e32 v130, 1.0, v130
	v_rcp_f32_e32 v130, v130
	s_nop 0
	v_mul_f32_e32 v169, v131, v130
	v_cvt_pk_bf16_f32 v130, v147, v164
	v_add_co_u32_e32 v164, vcc, s0, v158
	v_cvt_pk_bf16_f32 v131, v165, v167
	v_cvt_pk_bf16_f32 v132, v132, v133
	v_cvt_pk_bf16_f32 v133, v168, v169
	s_mov_b64 s[0:1], 0x280000
	s_nop 0
	v_addc_co_u32_e32 v165, vcc, 0, v159, vcc
	global_store_dwordx4 v[164:165], v[130:133], off
	s_nop 1
	v_pk_mul_f32 v[132:133], v[38:39], v[0:1] op_sel_hi:[1,0]
	v_pk_mul_f32 v[130:131], v[40:41], v[0:1] op_sel_hi:[1,0]
	v_mul_f32_e32 v147, 0xbfb8aa3b, v132
	v_exp_f32_e32 v147, v147
	s_nop 0
	v_add_f32_e32 v147, 1.0, v147
	v_rcp_f32_e32 v147, v147
	s_nop 0
	v_mul_f32_e32 v147, v132, v147
	v_mul_f32_e32 v132, 0xbfb8aa3b, v133
	v_exp_f32_e32 v132, v132
	s_nop 0
	v_add_f32_e32 v132, 1.0, v132
	v_rcp_f32_e32 v132, v132
	s_nop 0
	v_mul_f32_e32 v164, v133, v132
	v_mul_f32_e32 v132, 0xbfb8aa3b, v130
	v_exp_f32_e32 v132, v132
	s_nop 0
	v_add_f32_e32 v132, 1.0, v132
	v_rcp_f32_e32 v132, v132
	s_nop 0
	v_mul_f32_e32 v165, v130, v132
	v_mul_f32_e32 v130, 0xbfb8aa3b, v131
	v_exp_f32_e32 v130, v130
	v_pk_mul_f32 v[132:133], v[34:35], v[0:1] op_sel_hi:[1,0]
	v_add_f32_e32 v130, 1.0, v130
	v_rcp_f32_e32 v130, v130
	s_nop 0
	v_mul_f32_e32 v167, v131, v130
	v_pk_mul_f32 v[130:131], v[36:37], v[0:1] op_sel_hi:[1,0]
	v_mul_f32_e32 v0, 0xbfb8aa3b, v132
	v_exp_f32_e32 v0, v0
	s_nop 0
	v_add_f32_e32 v0, 1.0, v0
	v_rcp_f32_e32 v0, v0
	s_nop 0
	v_mul_f32_e32 v0, v132, v0
	v_mul_f32_e32 v132, 0xbfb8aa3b, v133
	v_exp_f32_e32 v132, v132
	s_nop 0
	v_add_f32_e32 v132, 1.0, v132
	v_rcp_f32_e32 v132, v132
	s_nop 0
	v_mul_f32_e32 v132, v133, v132
	v_mul_f32_e32 v133, 0xbfb8aa3b, v130
	v_exp_f32_e32 v133, v133
	s_nop 0
	v_add_f32_e32 v133, 1.0, v133
	v_rcp_f32_e32 v133, v133
	s_nop 0
	v_mul_f32_e32 v133, v130, v133
	v_mul_f32_e32 v130, 0xbfb8aa3b, v131
	v_exp_f32_e32 v130, v130
	s_nop 0
	v_add_f32_e32 v130, 1.0, v130
	v_rcp_f32_e32 v130, v130
	s_nop 0
	v_mul_f32_e32 v168, v131, v130
	v_cvt_pk_bf16_f32 v130, v147, v164
	v_cvt_pk_bf16_f32 v131, v165, v167
	v_cvt_pk_bf16_f32 v132, v0, v132
	v_cvt_pk_bf16_f32 v133, v133, v168
	global_store_dwordx4 v[162:163], v[130:133], off offset:256
	v_mov_b32_e32 v0, v234
	v_fmamk_f32 v0, v0, 0x3a000000, v197
	v_cmp_gt_f32_e32 vcc, s81, v0
	v_mul_f32_e32 v130, 0x4b800000, v0
	s_nop 0
	v_cndmask_b32_e32 v0, v0, v130, vcc
	v_rsq_f32_e32 v0, v0
	s_nop 0
	v_mul_f32_e32 v130, 0x45800000, v0
	v_cndmask_b32_e32 v0, v0, v130, vcc
	v_pk_mul_f32 v[162:163], v[30:31], v[0:1] op_sel_hi:[1,0]
	v_pk_mul_f32 v[132:133], v[32:33], v[0:1] op_sel_hi:[1,0]
	v_mul_f32_e32 v147, 0xbfb8aa3b, v162
	v_exp_f32_e32 v147, v147
	v_lshl_add_u64 v[130:131], v[158:159], 0, s[0:1]
	s_mov_b32 s0, 0x280000
	v_add_f32_e32 v147, 1.0, v147
	v_rcp_f32_e32 v147, v147
	s_nop 0
	v_mul_f32_e32 v147, v162, v147
	v_mul_f32_e32 v162, 0xbfb8aa3b, v163
	v_exp_f32_e32 v162, v162
	s_nop 0
	v_add_f32_e32 v162, 1.0, v162
	v_rcp_f32_e32 v162, v162
	s_nop 0
	v_mul_f32_e32 v164, v163, v162
	v_mul_f32_e32 v162, 0xbfb8aa3b, v132
	v_exp_f32_e32 v162, v162
	s_nop 0
	v_add_f32_e32 v162, 1.0, v162
	v_rcp_f32_e32 v162, v162
	s_nop 0
	v_mul_f32_e32 v165, v132, v162
	v_pk_mul_f32 v[162:163], v[26:27], v[0:1] op_sel_hi:[1,0]
	v_mul_f32_e32 v132, 0xbfb8aa3b, v133
	v_mul_f32_e32 v168, 0xbfb8aa3b, v162
	v_exp_f32_e32 v168, v168
	v_exp_f32_e32 v132, v132
	v_add_f32_e32 v168, 1.0, v168
	v_rcp_f32_e32 v168, v168
	v_add_f32_e32 v132, 1.0, v132
	v_rcp_f32_e32 v132, v132
	v_mul_f32_e32 v168, v162, v168
	v_mul_f32_e32 v162, 0xbfb8aa3b, v163
	v_exp_f32_e32 v162, v162
	v_mul_f32_e32 v167, v133, v132
	v_pk_mul_f32 v[132:133], v[28:29], v[0:1] op_sel_hi:[1,0]
	v_add_f32_e32 v162, 1.0, v162
	v_rcp_f32_e32 v162, v162
	s_nop 0
	v_mul_f32_e32 v169, v163, v162
	v_mul_f32_e32 v162, 0xbfb8aa3b, v132
	v_exp_f32_e32 v162, v162
	s_nop 0
	v_add_f32_e32 v162, 1.0, v162
	v_rcp_f32_e32 v162, v162
	s_nop 0
	v_mul_f32_e32 v132, v132, v162
	v_mul_f32_e32 v162, 0xbfb8aa3b, v133
	v_exp_f32_e32 v162, v162
	s_nop 0
	v_add_f32_e32 v162, 1.0, v162
	v_rcp_f32_e32 v162, v162
	s_nop 0
	v_mul_f32_e32 v133, v133, v162
	v_cvt_pk_bf16_f32 v162, v147, v164
	v_cvt_pk_bf16_f32 v163, v165, v167
	v_cvt_pk_bf16_f32 v164, v168, v169
	v_cvt_pk_bf16_f32 v165, v132, v133
	v_add_co_u32_e32 v132, vcc, s0, v158
	s_mov_b64 s[0:1], 0x2c0000
	s_nop 0
	v_addc_co_u32_e32 v133, vcc, 0, v159, vcc
	global_store_dwordx4 v[132:133], v[162:165], off
	v_pk_mul_f32 v[132:133], v[24:25], v[0:1] op_sel_hi:[1,0]
	s_nop 0
	v_pk_mul_f32 v[162:163], v[22:23], v[0:1] op_sel_hi:[1,0]
	s_nop 0
	v_mul_f32_e32 v147, 0xbfb8aa3b, v162
	v_exp_f32_e32 v147, v147
	s_nop 0
	v_add_f32_e32 v147, 1.0, v147
	v_rcp_f32_e32 v147, v147
	s_nop 0
	v_mul_f32_e32 v147, v162, v147
	v_mul_f32_e32 v162, 0xbfb8aa3b, v163
	v_exp_f32_e32 v162, v162
	s_nop 0
	v_add_f32_e32 v162, 1.0, v162
	v_rcp_f32_e32 v162, v162
	s_nop 0
	v_mul_f32_e32 v164, v163, v162
	v_mul_f32_e32 v162, 0xbfb8aa3b, v132
	v_exp_f32_e32 v162, v162
	s_nop 0
	v_add_f32_e32 v162, 1.0, v162
	v_rcp_f32_e32 v162, v162
	s_nop 0
	v_mul_f32_e32 v165, v132, v162
	v_mul_f32_e32 v132, 0xbfb8aa3b, v133
	v_exp_f32_e32 v132, v132
	v_pk_mul_f32 v[162:163], v[18:19], v[0:1] op_sel_hi:[1,0]
	v_add_f32_e32 v132, 1.0, v132
	v_rcp_f32_e32 v132, v132
	s_nop 0
	v_mul_f32_e32 v167, v133, v132
	v_pk_mul_f32 v[132:133], v[20:21], v[0:1] op_sel_hi:[1,0]
	v_mul_f32_e32 v0, 0xbfb8aa3b, v162
	v_exp_f32_e32 v0, v0
	s_nop 0
	v_add_f32_e32 v0, 1.0, v0
	v_rcp_f32_e32 v0, v0
	s_nop 0
	v_mul_f32_e32 v0, v162, v0
	v_mul_f32_e32 v162, 0xbfb8aa3b, v163
	v_exp_f32_e32 v162, v162
	s_nop 0
	v_add_f32_e32 v162, 1.0, v162
	v_rcp_f32_e32 v162, v162
	s_nop 0
	v_mul_f32_e32 v168, v163, v162
	v_mul_f32_e32 v162, 0xbfb8aa3b, v132
	v_exp_f32_e32 v162, v162
	s_nop 0
	v_add_f32_e32 v162, 1.0, v162
	v_rcp_f32_e32 v162, v162
	s_nop 0
	v_mul_f32_e32 v132, v132, v162
	v_mul_f32_e32 v162, 0xbfb8aa3b, v133
	v_exp_f32_e32 v162, v162
	s_nop 0
	v_add_f32_e32 v162, 1.0, v162
	v_rcp_f32_e32 v162, v162
	s_nop 0
	v_mul_f32_e32 v133, v133, v162
	v_cvt_pk_bf16_f32 v162, v147, v164
	v_cvt_pk_bf16_f32 v163, v165, v167
	v_cvt_pk_bf16_f32 v164, v0, v168
	v_cvt_pk_bf16_f32 v165, v132, v133
	global_store_dwordx4 v[130:131], v[162:165], off offset:256
	v_mov_b32_e32 v0, v235
	v_fmamk_f32 v0, v0, 0x3a000000, v197
	v_cmp_gt_f32_e32 vcc, s81, v0
	v_mul_f32_e32 v130, 0x4b800000, v0
	s_nop 0
	v_cndmask_b32_e32 v0, v0, v130, vcc
	v_rsq_f32_e32 v0, v0
	s_nop 0
	v_mul_f32_e32 v130, 0x45800000, v0
	v_cndmask_b32_e32 v0, v0, v130, vcc
	v_pk_mul_f32 v[160:161], v[14:15], v[0:1] op_sel_hi:[1,0]
	v_pk_mul_f32 v[132:133], v[16:17], v[0:1] op_sel_hi:[1,0]
	v_mul_f32_e32 v147, 0xbfb8aa3b, v160
	v_exp_f32_e32 v147, v147
	v_lshl_add_u64 v[130:131], v[158:159], 0, s[0:1]
	s_mov_b32 s0, 0x2c0000
	v_add_f32_e32 v147, 1.0, v147
	v_rcp_f32_e32 v147, v147
	s_nop 0
	v_mul_f32_e32 v147, v160, v147
	v_mul_f32_e32 v160, 0xbfb8aa3b, v161
	v_exp_f32_e32 v160, v160
	s_nop 0
	v_add_f32_e32 v160, 1.0, v160
	v_rcp_f32_e32 v160, v160
	s_nop 0
	v_mul_f32_e32 v162, v161, v160
	v_mul_f32_e32 v160, 0xbfb8aa3b, v132
	v_exp_f32_e32 v160, v160
	s_nop 0
	v_add_f32_e32 v160, 1.0, v160
	v_rcp_f32_e32 v160, v160
	s_nop 0
	v_mul_f32_e32 v163, v132, v160
	v_pk_mul_f32 v[160:161], v[10:11], v[0:1] op_sel_hi:[1,0]
	v_mul_f32_e32 v132, 0xbfb8aa3b, v133
	v_mul_f32_e32 v165, 0xbfb8aa3b, v160
	v_exp_f32_e32 v165, v165
	v_exp_f32_e32 v132, v132
	v_add_f32_e32 v165, 1.0, v165
	v_rcp_f32_e32 v165, v165
	v_add_f32_e32 v132, 1.0, v132
	v_rcp_f32_e32 v132, v132
	v_mul_f32_e32 v165, v160, v165
	v_mul_f32_e32 v160, 0xbfb8aa3b, v161
	v_exp_f32_e32 v160, v160
	v_mul_f32_e32 v164, v133, v132
	v_pk_mul_f32 v[132:133], v[12:13], v[0:1] op_sel_hi:[1,0]
	v_add_f32_e32 v160, 1.0, v160
	v_rcp_f32_e32 v160, v160
	s_nop 0
	v_mul_f32_e32 v167, v161, v160
	v_mul_f32_e32 v160, 0xbfb8aa3b, v132
	v_exp_f32_e32 v160, v160
	s_nop 0
	v_add_f32_e32 v160, 1.0, v160
	v_rcp_f32_e32 v160, v160
	s_nop 0
	v_mul_f32_e32 v132, v132, v160
	v_mul_f32_e32 v160, 0xbfb8aa3b, v133
	v_exp_f32_e32 v160, v160
	s_nop 0
	v_add_f32_e32 v160, 1.0, v160
	v_rcp_f32_e32 v160, v160
	s_nop 0
	v_mul_f32_e32 v133, v133, v160
	v_cvt_pk_bf16_f32 v160, v147, v162
	v_cvt_pk_bf16_f32 v161, v163, v164
	v_cvt_pk_bf16_f32 v162, v165, v167
	v_cvt_pk_bf16_f32 v163, v132, v133
	v_add_co_u32_e32 v132, vcc, s0, v158
	s_mov_b64 s[0:1], 0
	s_nop 0
	v_addc_co_u32_e32 v133, vcc, 0, v159, vcc
	v_pk_mul_f32 v[158:159], v[6:7], v[0:1] op_sel_hi:[1,0]
	global_store_dwordx4 v[132:133], v[160:163], off
	v_mul_f32_e32 v147, 0xbfb8aa3b, v158
	v_exp_f32_e32 v147, v147
	v_pk_mul_f32 v[132:133], v[8:9], v[0:1] op_sel_hi:[1,0]
	v_add_f32_e32 v147, 1.0, v147
	v_rcp_f32_e32 v147, v147
	s_nop 0
	v_mul_f32_e32 v147, v158, v147
	v_mul_f32_e32 v158, 0xbfb8aa3b, v159
	v_exp_f32_e32 v158, v158
	s_nop 0
	v_add_f32_e32 v158, 1.0, v158
	v_rcp_f32_e32 v158, v158
	s_nop 0
	v_mul_f32_e32 v160, v159, v158
	v_mul_f32_e32 v158, 0xbfb8aa3b, v132
	v_exp_f32_e32 v158, v158
	s_nop 0
	v_add_f32_e32 v158, 1.0, v158
	v_rcp_f32_e32 v158, v158
	s_nop 0
	v_mul_f32_e32 v161, v132, v158
	v_mul_f32_e32 v132, 0xbfb8aa3b, v133
	v_exp_f32_e32 v132, v132
	v_pk_mul_f32 v[158:159], v[2:3], v[0:1] op_sel_hi:[1,0]
	v_add_f32_e32 v132, 1.0, v132
	v_rcp_f32_e32 v132, v132
	s_nop 0
	v_mul_f32_e32 v162, v133, v132
	v_pk_mul_f32 v[132:133], v[4:5], v[0:1] op_sel_hi:[1,0]
	v_mul_f32_e32 v0, 0xbfb8aa3b, v158
	v_exp_f32_e32 v0, v0
	s_nop 0
	v_add_f32_e32 v0, 1.0, v0
	v_rcp_f32_e32 v0, v0
	s_nop 0
	v_mul_f32_e32 v0, v158, v0
	v_mul_f32_e32 v158, 0xbfb8aa3b, v159
	v_exp_f32_e32 v158, v158
	s_nop 0
	v_add_f32_e32 v158, 1.0, v158
	v_rcp_f32_e32 v158, v158
	s_nop 0
	v_mul_f32_e32 v163, v159, v158
	v_mul_f32_e32 v158, 0xbfb8aa3b, v132
	v_exp_f32_e32 v158, v158
	s_nop 0
	v_add_f32_e32 v158, 1.0, v158
	v_rcp_f32_e32 v158, v158
	s_nop 0
	v_mul_f32_e32 v132, v132, v158
	v_mul_f32_e32 v158, 0xbfb8aa3b, v133
	v_exp_f32_e32 v158, v158
	s_nop 0
	v_add_f32_e32 v158, 1.0, v158
	v_rcp_f32_e32 v158, v158
	s_nop 0
	v_mul_f32_e32 v133, v133, v158
	v_cvt_pk_bf16_f32 v158, v147, v160
	v_cvt_pk_bf16_f32 v159, v161, v162
	v_cvt_pk_bf16_f32 v160, v0, v163
	v_cvt_pk_bf16_f32 v161, v132, v133
	global_store_dwordx4 v[130:131], v[158:161], off offset:256

.LBB0_142:
	v_or_b32_e32 v147, s79, v166
	v_add_u32_e32 v172, s21, v147
	v_ashrrev_i32_e32 v173, 31, v172
	v_lshl_add_u64 v[130:131], v[172:173], 2, s[12:13]
	global_load_dword v0, v[130:131], off
	global_load_dword v229, v[130:131], off offset:64
	global_load_dword v230, v[130:131], off offset:128
	global_load_dword v231, v[130:131], off offset:192
	global_load_dword v232, v[130:131], off offset:512
	global_load_dword v233, v[130:131], off offset:576
	global_load_dword v234, v[130:131], off offset:640
	global_load_dword v235, v[130:131], off offset:704
	v_and_b32_e32 v131, 64, v200
	v_xor_b32_e32 v130, 16, v200
	v_add_u32_e32 v131, 64, v131
	v_cmp_lt_i32_e64 s[4:5], v130, v131
	v_lshlrev_b32_e32 v217, 5, v147
	v_readlane_b32 s0, v251, 22
	s_waitcnt vmcnt(0)
	v_fmamk_f32 v0, v0, 0x3a000000, v197
	v_mul_f32_e32 v132, 0x4b800000, v0
	v_cmp_gt_f32_e32 vcc, s81, v0
	s_nop 1
	v_cndmask_b32_e32 v0, v0, v132, vcc
	v_rsq_f32_e32 v132, v0
	v_cndmask_b32_e64 v0, v200, v130, s[4:5]
	v_lshlrev_b32_e32 v0, 2, v0
	v_mul_f32_e32 v130, 0x45800000, v132
	v_cndmask_b32_e32 v130, v132, v130, vcc
	v_pk_mul_f32 v[188:189], v[126:127], v[130:131] op_sel_hi:[1,0]
	v_pk_mul_f32 v[174:175], v[122:123], v[130:131] op_sel_hi:[1,0]
	v_mul_f32_e32 v122, v189, v189
	v_pk_mul_f32 v[178:179], v[128:129], v[130:131] op_sel_hi:[1,0]
	v_fmac_f32_e32 v122, v188, v188
	v_fmac_f32_e32 v122, v178, v178
	v_fmac_f32_e32 v122, v179, v179
	v_fmac_f32_e32 v122, v174, v174
	v_pk_mul_f32 v[176:177], v[124:125], v[130:131] op_sel_hi:[1,0]
	v_fmac_f32_e32 v122, v175, v175
	v_fmac_f32_e32 v122, v176, v176
	v_fmac_f32_e32 v122, v177, v177
	ds_bpermute_b32 v123, v0, v122
	v_xor_b32_e32 v124, 32, v200
	v_cmp_lt_i32_e32 vcc, v124, v131
	s_waitcnt lgkmcnt(0)
	v_add_f32_e32 v123, v122, v123
	v_cndmask_b32_e32 v124, v200, v124, vcc
	v_lshlrev_b32_e32 v207, 2, v124
	ds_bpermute_b32 v124, v207, v123
	v_cmp_gt_u32_e32 vcc, 16, v149
	v_add_u32_e32 v122, s0, v217
	s_and_saveexec_b64 s[0:1], vcc
	s_cbranch_execz .LBB0_144
	s_waitcnt lgkmcnt(0)
	v_add_f32_e32 v123, v123, v124
	ds_write_b32 v122, v123

.LBB0_146:
	s_or_b64 exec, exec, s[0:1]
	v_or_b32_e32 v116, 16, v147
	v_add_u32_e32 v130, s21, v116
	v_ashrrev_i32_e32 v131, 31, v130
	s_waitcnt lgkmcnt(0)
	v_lshl_add_u64 v[114:115], v[130:131], 2, s[12:13]
	v_mov_b32_e32 v114, v229
	v_lshlrev_b32_e32 v216, 5, v116
	v_readlane_b32 s0, v251, 22
	v_fmamk_f32 v114, v114, 0x3a000000, v197
	v_mul_f32_e32 v115, 0x4b800000, v114
	v_cmp_gt_f32_e64 s[4:5], s81, v114
	s_nop 1
	v_cndmask_b32_e64 v114, v114, v115, s[4:5]
	v_rsq_f32_e32 v114, v114
	s_nop 0
	v_mul_f32_e32 v115, 0x45800000, v114
	v_cndmask_b32_e64 v114, v114, v115, s[4:5]
	v_pk_mul_f32 v[162:163], v[110:111], v[114:115] op_sel_hi:[1,0]
	v_pk_mul_f32 v[156:157], v[106:107], v[114:115] op_sel_hi:[1,0]
	v_mul_f32_e32 v106, v163, v163
	v_pk_mul_f32 v[160:161], v[112:113], v[114:115] op_sel_hi:[1,0]
	v_fmac_f32_e32 v106, v162, v162
	v_fmac_f32_e32 v106, v160, v160
	v_fmac_f32_e32 v106, v161, v161
	v_fmac_f32_e32 v106, v156, v156
	v_pk_mul_f32 v[158:159], v[108:109], v[114:115] op_sel_hi:[1,0]
	v_fmac_f32_e32 v106, v157, v157
	v_fmac_f32_e32 v106, v158, v158
	v_fmac_f32_e32 v106, v159, v159
	ds_bpermute_b32 v107, v0, v106
	s_waitcnt lgkmcnt(0)
	v_add_f32_e32 v107, v106, v107
	ds_bpermute_b32 v108, v207, v107
	v_add_u32_e32 v106, s0, v216
	s_and_saveexec_b64 s[0:1], vcc
	s_cbranch_execz .LBB0_148
	s_waitcnt lgkmcnt(0)
	v_add_f32_e32 v107, v107, v108
	ds_write_b32 v106, v107

.LBB0_150:
	s_or_b64 exec, exec, s[0:1]
	v_or_b32_e32 v100, 32, v147
	v_add_u32_e32 v112, s21, v100
	v_ashrrev_i32_e32 v113, 31, v112
	s_waitcnt lgkmcnt(0)
	v_lshl_add_u64 v[98:99], v[112:113], 2, s[12:13]
	v_mov_b32_e32 v98, v230
	v_lshlrev_b32_e32 v215, 5, v100
	v_readlane_b32 s0, v251, 22
	v_fmamk_f32 v98, v98, 0x3a000000, v197
	v_mul_f32_e32 v99, 0x4b800000, v98
	v_cmp_gt_f32_e64 s[4:5], s81, v98
	s_nop 1
	v_cndmask_b32_e64 v98, v98, v99, s[4:5]
	v_rsq_f32_e32 v98, v98
	s_nop 0
	v_mul_f32_e32 v99, 0x45800000, v98
	v_cndmask_b32_e64 v98, v98, v99, s[4:5]
	v_pk_mul_f32 v[128:129], v[94:95], v[98:99] op_sel_hi:[1,0]
	v_pk_mul_f32 v[122:123], v[90:91], v[98:99] op_sel_hi:[1,0]
	v_mul_f32_e32 v90, v129, v129
	v_pk_mul_f32 v[126:127], v[96:97], v[98:99] op_sel_hi:[1,0]
	v_fmac_f32_e32 v90, v128, v128
	v_fmac_f32_e32 v90, v126, v126
	v_fmac_f32_e32 v90, v127, v127
	v_fmac_f32_e32 v90, v122, v122
	v_pk_mul_f32 v[124:125], v[92:93], v[98:99] op_sel_hi:[1,0]
	v_fmac_f32_e32 v90, v123, v123
	v_fmac_f32_e32 v90, v124, v124
	v_fmac_f32_e32 v90, v125, v125
	ds_bpermute_b32 v91, v0, v90
	s_waitcnt lgkmcnt(0)
	v_add_f32_e32 v91, v90, v91
	ds_bpermute_b32 v92, v207, v91
	v_add_u32_e32 v90, s0, v215
	s_and_saveexec_b64 s[0:1], vcc
	s_cbranch_execz .LBB0_152
	s_waitcnt lgkmcnt(0)
	v_add_f32_e32 v91, v91, v92
	ds_write_b32 v90, v91

.LBB0_154:
	s_or_b64 exec, exec, s[0:1]
	v_or_b32_e32 v84, 48, v147
	v_add_u32_e32 v94, s21, v84
	v_ashrrev_i32_e32 v95, 31, v94
	s_waitcnt lgkmcnt(0)
	v_lshl_add_u64 v[82:83], v[94:95], 2, s[12:13]
	v_mov_b32_e32 v82, v231
	v_lshlrev_b32_e32 v214, 5, v84
	v_readlane_b32 s0, v251, 22
	v_fmamk_f32 v82, v82, 0x3a000000, v197
	v_mul_f32_e32 v83, 0x4b800000, v82
	v_cmp_gt_f32_e64 s[4:5], s81, v82
	s_nop 1
	v_cndmask_b32_e64 v82, v82, v83, s[4:5]
	v_rsq_f32_e32 v82, v82
	s_nop 0
	v_mul_f32_e32 v83, 0x45800000, v82
	v_cndmask_b32_e64 v82, v82, v83, s[4:5]
	v_pk_mul_f32 v[110:111], v[78:79], v[82:83] op_sel_hi:[1,0]
	v_pk_mul_f32 v[104:105], v[74:75], v[82:83] op_sel_hi:[1,0]
	v_mul_f32_e32 v74, v111, v111
	v_pk_mul_f32 v[108:109], v[80:81], v[82:83] op_sel_hi:[1,0]
	v_fmac_f32_e32 v74, v110, v110
	v_fmac_f32_e32 v74, v108, v108
	v_fmac_f32_e32 v74, v109, v109
	v_fmac_f32_e32 v74, v104, v104
	v_pk_mul_f32 v[106:107], v[76:77], v[82:83] op_sel_hi:[1,0]
	v_fmac_f32_e32 v74, v105, v105
	v_fmac_f32_e32 v74, v106, v106
	v_fmac_f32_e32 v74, v107, v107
	ds_bpermute_b32 v75, v0, v74
	s_waitcnt lgkmcnt(0)
	v_add_f32_e32 v75, v74, v75
	ds_bpermute_b32 v76, v207, v75
	v_add_u32_e32 v74, s0, v214
	s_and_saveexec_b64 s[0:1], vcc
	s_cbranch_execz .LBB0_156
	s_waitcnt lgkmcnt(0)
	v_add_f32_e32 v75, v75, v76
	ds_write_b32 v74, v75

.LBB0_158:
	s_or_b64 exec, exec, s[0:1]
	v_add_u32_e32 v68, 0x80, v147
	v_add_u32_e32 v76, s21, v68
	v_ashrrev_i32_e32 v77, 31, v76
	s_waitcnt lgkmcnt(0)
	v_lshl_add_u64 v[66:67], v[76:77], 2, s[12:13]
	v_mov_b32_e32 v66, v232
	v_lshlrev_b32_e32 v213, 5, v68
	v_readlane_b32 s0, v251, 22
	v_fmamk_f32 v66, v66, 0x3a000000, v197
	v_mul_f32_e32 v67, 0x4b800000, v66
	v_cmp_gt_f32_e64 s[4:5], s81, v66
	s_nop 1
	v_cndmask_b32_e64 v66, v66, v67, s[4:5]
	v_rsq_f32_e32 v66, v66
	s_nop 0
	v_mul_f32_e32 v67, 0x45800000, v66
	v_cndmask_b32_e64 v66, v66, v67, s[4:5]
	v_pk_mul_f32 v[92:93], v[62:63], v[66:67] op_sel_hi:[1,0]
	v_pk_mul_f32 v[86:87], v[58:59], v[66:67] op_sel_hi:[1,0]
	v_mul_f32_e32 v58, v93, v93
	v_pk_mul_f32 v[90:91], v[64:65], v[66:67] op_sel_hi:[1,0]
	v_fmac_f32_e32 v58, v92, v92
	v_fmac_f32_e32 v58, v90, v90
	v_fmac_f32_e32 v58, v91, v91
	v_fmac_f32_e32 v58, v86, v86
	v_pk_mul_f32 v[88:89], v[60:61], v[66:67] op_sel_hi:[1,0]
	v_fmac_f32_e32 v58, v87, v87
	v_fmac_f32_e32 v58, v88, v88
	v_fmac_f32_e32 v58, v89, v89
	ds_bpermute_b32 v59, v0, v58
	s_waitcnt lgkmcnt(0)
	v_add_f32_e32 v59, v58, v59
	ds_bpermute_b32 v60, v207, v59
	v_add_u32_e32 v58, s0, v213
	s_and_saveexec_b64 s[0:1], vcc
	s_cbranch_execz .LBB0_160
	s_waitcnt lgkmcnt(0)
	v_add_f32_e32 v59, v59, v60
	ds_write_b32 v58, v59

.LBB0_162:
	s_or_b64 exec, exec, s[0:1]
	v_add_u32_e32 v52, 0x90, v147
	v_add_u32_e32 v58, s21, v52
	v_ashrrev_i32_e32 v59, 31, v58
	s_waitcnt lgkmcnt(0)
	v_lshl_add_u64 v[50:51], v[58:59], 2, s[12:13]
	v_mov_b32_e32 v50, v233
	v_lshlrev_b32_e32 v212, 5, v52
	v_readlane_b32 s0, v251, 22
	v_fmamk_f32 v50, v50, 0x3a000000, v197
	v_mul_f32_e32 v51, 0x4b800000, v50
	v_cmp_gt_f32_e64 s[4:5], s81, v50
	s_nop 1
	v_cndmask_b32_e64 v50, v50, v51, s[4:5]
	v_rsq_f32_e32 v50, v50
	s_nop 0
	v_mul_f32_e32 v51, 0x45800000, v50
	v_cndmask_b32_e64 v50, v50, v51, s[4:5]
	v_pk_mul_f32 v[74:75], v[46:47], v[50:51] op_sel_hi:[1,0]
	v_pk_mul_f32 v[68:69], v[42:43], v[50:51] op_sel_hi:[1,0]
	v_mul_f32_e32 v42, v75, v75
	v_pk_mul_f32 v[72:73], v[48:49], v[50:51] op_sel_hi:[1,0]
	v_fmac_f32_e32 v42, v74, v74
	v_fmac_f32_e32 v42, v72, v72
	v_fmac_f32_e32 v42, v73, v73
	v_fmac_f32_e32 v42, v68, v68
	v_pk_mul_f32 v[70:71], v[44:45], v[50:51] op_sel_hi:[1,0]
	v_fmac_f32_e32 v42, v69, v69
	v_fmac_f32_e32 v42, v70, v70
	v_fmac_f32_e32 v42, v71, v71
	ds_bpermute_b32 v43, v0, v42
	s_waitcnt lgkmcnt(0)
	v_add_f32_e32 v43, v42, v43
	ds_bpermute_b32 v44, v207, v43
	v_add_u32_e32 v42, s0, v212
	s_and_saveexec_b64 s[0:1], vcc
	s_cbranch_execz .LBB0_164
	s_waitcnt lgkmcnt(0)
	v_add_f32_e32 v43, v43, v44
	ds_write_b32 v42, v43

.LBB0_166:
	s_or_b64 exec, exec, s[0:1]
	v_add_u32_e32 v36, 0xa0, v147
	v_add_u32_e32 v40, s21, v36
	v_ashrrev_i32_e32 v41, 31, v40
	s_waitcnt lgkmcnt(0)
	v_lshl_add_u64 v[34:35], v[40:41], 2, s[12:13]
	v_mov_b32_e32 v34, v234
	v_lshlrev_b32_e32 v210, 5, v36
	v_readlane_b32 s0, v251, 22
	v_fmamk_f32 v34, v34, 0x3a000000, v197
	v_mul_f32_e32 v35, 0x4b800000, v34
	v_cmp_gt_f32_e64 s[4:5], s81, v34
	s_nop 1
	v_cndmask_b32_e64 v34, v34, v35, s[4:5]
	v_rsq_f32_e32 v34, v34
	s_nop 0
	v_mul_f32_e32 v35, 0x45800000, v34
	v_cndmask_b32_e64 v34, v34, v35, s[4:5]
	v_pk_mul_f32 v[56:57], v[30:31], v[34:35] op_sel_hi:[1,0]
	v_pk_mul_f32 v[50:51], v[26:27], v[34:35] op_sel_hi:[1,0]
	v_mul_f32_e32 v26, v57, v57
	v_pk_mul_f32 v[54:55], v[32:33], v[34:35] op_sel_hi:[1,0]
	v_fmac_f32_e32 v26, v56, v56
	v_fmac_f32_e32 v26, v54, v54
	v_fmac_f32_e32 v26, v55, v55
	v_fmac_f32_e32 v26, v50, v50
	v_pk_mul_f32 v[52:53], v[28:29], v[34:35] op_sel_hi:[1,0]
	v_fmac_f32_e32 v26, v51, v51
	v_fmac_f32_e32 v26, v52, v52
	v_fmac_f32_e32 v26, v53, v53
	ds_bpermute_b32 v27, v0, v26
	s_waitcnt lgkmcnt(0)
	v_add_f32_e32 v27, v26, v27
	ds_bpermute_b32 v28, v207, v27
	v_add_u32_e32 v26, s0, v210
	s_and_saveexec_b64 s[0:1], vcc
	s_cbranch_execz .LBB0_168
	s_waitcnt lgkmcnt(0)
	v_add_f32_e32 v27, v27, v28
	ds_write_b32 v26, v27

.LBB0_170:
	s_or_b64 exec, exec, s[0:1]
	v_add_u32_e32 v20, 0xb0, v147
	v_add_u32_e32 v22, s21, v20
	v_ashrrev_i32_e32 v23, 31, v22
	s_waitcnt lgkmcnt(0)
	v_lshl_add_u64 v[18:19], v[22:23], 2, s[12:13]
	v_mov_b32_e32 v18, v235
	v_lshlrev_b32_e32 v208, 5, v20
	v_readlane_b32 s0, v251, 22
	v_fmamk_f32 v18, v18, 0x3a000000, v197
	v_mul_f32_e32 v19, 0x4b800000, v18
	v_cmp_gt_f32_e64 s[4:5], s81, v18
	s_nop 1
	v_cndmask_b32_e64 v18, v18, v19, s[4:5]
	v_rsq_f32_e32 v18, v18
	s_nop 0
	v_mul_f32_e32 v19, 0x45800000, v18
	v_cndmask_b32_e64 v18, v18, v19, s[4:5]
	v_pk_mul_f32 v[38:39], v[14:15], v[18:19] op_sel_hi:[1,0]
	v_pk_mul_f32 v[32:33], v[10:11], v[18:19] op_sel_hi:[1,0]
	v_mul_f32_e32 v10, v39, v39
	v_pk_mul_f32 v[36:37], v[16:17], v[18:19] op_sel_hi:[1,0]
	v_fmac_f32_e32 v10, v38, v38
	v_fmac_f32_e32 v10, v36, v36
	v_fmac_f32_e32 v10, v37, v37
	v_fmac_f32_e32 v10, v32, v32
	v_pk_mul_f32 v[34:35], v[12:13], v[18:19] op_sel_hi:[1,0]
	v_fmac_f32_e32 v10, v33, v33
	v_fmac_f32_e32 v10, v34, v34
	v_fmac_f32_e32 v10, v35, v35
	ds_bpermute_b32 v11, v0, v10
	s_waitcnt lgkmcnt(0)
	v_add_f32_e32 v11, v10, v11
	ds_bpermute_b32 v12, v207, v11
	v_add_u32_e32 v10, s0, v208
	s_and_saveexec_b64 s[0:1], vcc
	s_cbranch_execz .LBB0_172
	s_waitcnt lgkmcnt(0)
	v_add_f32_e32 v11, v11, v12
	ds_write_b32 v10, v11

.LBB0_1279:
	s_lshl_b32 s15, s54, 8
	s_add_i32 s15, s15, s79
	v_mbcnt_lo_u32_b32 v156, -1, 0
	v_mbcnt_hi_u32_b32 v156, -1, v156
	v_readlane_b32 s17, v252, 33
	v_and_or_b32 v140, v156, 15, s15
	s_lshl_b32 s15, s53, 8
	v_ashrrev_i32_e32 v141, 1, v156
	s_or_b32 s15, s15, s17
	v_and_b32_e32 v141, -8, v141
	v_add_u32_e32 v146, s15, v141
	v_ashrrev_i32_e32 v141, 31, v140
	v_ashrrev_i32_e32 v147, 31, v146
	v_lshlrev_b64 v[142:143], 11, v[140:141]
	v_lshl_add_u64 v[144:145], v[142:143], 0, v[146:147]
	v_lshlrev_b64 v[142:143], 2, v[144:145]
	v_lshl_add_u64 v[150:151], s[0:1], 0, v[142:143]
	global_load_dwordx4 v[158:161], v[150:151], off offset:16
	global_load_dwordx4 v[162:165], v[150:151], off
	v_lshl_add_u64 v[152:153], s[10:11], 0, v[142:143]
	v_cndmask_b32_e64 v142, 0, 1, s[12:13]
	v_cmp_ne_u32_e64 s[92:93], 1, v142
	s_andn2_b64 vcc, exec, s[12:13]
	v_lshl_add_u64 v[142:143], v[146:147], 2, s[4:5]
	v_lshl_add_u64 v[148:149], v[144:145], 1, s[6:7]
	s_waitcnt vmcnt(0)
	v_pk_add_f32 v[124:125], v[124:125], v[160:161]
	v_pk_add_f32 v[128:129], v[128:129], v[164:165]
	v_pk_add_f32 v[126:127], v[126:127], v[162:163]
	v_pk_add_f32 v[122:123], v[122:123], v[158:159]
	global_store_dwordx4 v[152:153], v[126:129], off
	global_store_dwordx4 v[152:153], v[122:125], off offset:16
	s_cbranch_vccnz .LBB0_1281
	global_load_dwordx4 v[234:237], v[142:143], off offset:16
	global_load_dwordx4 v[230:233], v[142:143], off
	global_load_dwordx4 v[242:245], v[142:143], off offset:528
	global_load_dwordx4 v[238:241], v[142:143], off offset:512
	s_waitcnt vmcnt(0)
	v_mov_b32_e32 v158, v234
	v_mov_b32_e32 v159, v235
	v_mov_b32_e32 v160, v236
	v_mov_b32_e32 v161, v237
	v_mov_b32_e32 v162, v230
	v_mov_b32_e32 v163, v231
	v_mov_b32_e32 v164, v232
	v_mov_b32_e32 v165, v233
	v_pk_mul_f32 v[166:167], v[124:125], v[160:161]
	v_pk_mul_f32 v[162:163], v[126:127], v[162:163]
	v_pk_mul_f32 v[126:127], v[126:127], v[126:127]
	v_pk_mul_f32 v[164:165], v[128:129], v[164:165]
	v_pk_mul_f32 v[128:129], v[128:129], v[128:129]
	v_add_f32_e32 v126, v126, v127
	v_add_f32_e32 v126, v128, v126
	v_pk_mul_f32 v[160:161], v[122:123], v[158:159]
	v_pk_mul_f32 v[122:123], v[122:123], v[122:123]
	v_add_f32_e32 v126, v129, v126
	v_add_f32_e32 v122, v122, v126
	v_pk_mul_f32 v[124:125], v[124:125], v[124:125]
	v_add_f32_e32 v122, v123, v122
	v_add_f32_e32 v122, v124, v122
	v_add_f32_e32 v122, v125, v122
	v_cvt_pk_bf16_f32 v158, v162, v163
	v_cvt_pk_bf16_f32 v159, v164, v165
	v_cvt_pk_bf16_f32 v160, v160, v161
	v_cvt_pk_bf16_f32 v161, v166, v167
	global_store_dwordx4 v[148:149], v[158:161], off
	s_branch .LBB0_1282

.LBB0_1282:
	v_cmp_gt_u32_e64 s[90:91], 16, v156
	global_load_dwordx4 v[124:127], v[150:151], off offset:528
	global_load_dwordx4 v[156:159], v[150:151], off offset:512
	s_and_b64 vcc, exec, s[92:93]
	s_waitcnt vmcnt(1)
	v_pk_add_f32 v[116:117], v[116:117], v[126:127]
	s_waitcnt vmcnt(0)
	v_pk_add_f32 v[120:121], v[120:121], v[158:159]
	v_pk_add_f32 v[118:119], v[118:119], v[156:157]
	v_pk_add_f32 v[114:115], v[114:115], v[124:125]
	global_store_dwordx4 v[152:153], v[118:121], off offset:512
	global_store_dwordx4 v[152:153], v[114:117], off offset:528
	s_cbranch_vccnz .LBB0_1286
	v_mov_b32_e32 v124, v242
	v_mov_b32_e32 v125, v243
	v_mov_b32_e32 v126, v244
	v_mov_b32_e32 v127, v245
	v_mov_b32_e32 v150, v238
	v_mov_b32_e32 v151, v239
	v_mov_b32_e32 v152, v240
	v_mov_b32_e32 v153, v241
	v_pk_mul_f32 v[150:151], v[118:119], v[150:151]
	v_mul_f32_e32 v119, v119, v119
	v_fmac_f32_e32 v119, v118, v118
	v_fmac_f32_e32 v119, v120, v120
	v_fmac_f32_e32 v119, v121, v121
	v_fmac_f32_e32 v119, v114, v114
	v_fmac_f32_e32 v119, v115, v115
	v_pk_mul_f32 v[128:129], v[120:121], v[152:153]
	v_pk_mul_f32 v[152:153], v[116:117], v[126:127]
	v_fmac_f32_e32 v119, v116, v116
	v_and_b32_e32 v116, 64, v200
	v_pk_mul_f32 v[126:127], v[114:115], v[124:125]
	v_xor_b32_e32 v115, 16, v200
	v_add_u32_e32 v116, 64, v116
	v_cmp_lt_i32_e32 vcc, v115, v116
	v_fmac_f32_e32 v119, v117, v117
	v_add_f32_e32 v114, v122, v119
	v_cndmask_b32_e32 v115, v200, v115, vcc
	v_lshlrev_b32_e32 v115, 2, v115
	ds_bpermute_b32 v115, v115, v114
	v_cvt_pk_bf16_f32 v124, v150, v151
	v_cvt_pk_bf16_f32 v125, v128, v129
	v_cvt_pk_bf16_f32 v126, v126, v127
	v_cvt_pk_bf16_f32 v127, v152, v153
	s_waitcnt lgkmcnt(0)
	v_add_f32_e32 v114, v114, v115
	v_xor_b32_e32 v115, 32, v200
	v_cmp_lt_i32_e32 vcc, v115, v116
	global_store_dwordx4 v[148:149], v[124:127], off offset:256
	s_nop 0
	v_cndmask_b32_e32 v115, v200, v115, vcc
	v_lshlrev_b32_e32 v115, 2, v115
	ds_bpermute_b32 v115, v115, v114
	s_and_saveexec_b64 s[22:23], s[90:91]
	s_cbranch_execz .LBB0_1285
	v_lshl_add_u64 v[116:117], v[140:141], 2, s[8:9]
	s_waitcnt lgkmcnt(0)
	v_add_f32_e32 v114, v114, v115
	global_atomic_add_f32 v[116:117], v114, off

.LBB0_1286:
	s_nop 0
	v_or_b32_e32 v114, 16, v140
	s_waitcnt lgkmcnt(0)
	v_ashrrev_i32_e32 v115, 31, v114
	v_lshlrev_b64 v[114:115], 11, v[114:115]
	v_lshl_add_u64 v[114:115], v[114:115], 0, v[146:147]
	v_lshlrev_b64 v[116:117], 2, v[114:115]
	v_lshl_add_u64 v[118:119], s[0:1], 0, v[116:117]
	global_load_dwordx4 v[120:123], v[118:119], off
	global_load_dwordx4 v[124:127], v[118:119], off offset:16
	s_and_b64 vcc, exec, s[92:93]
	v_lshl_add_u64 v[116:117], s[10:11], 0, v[116:117]
	v_lshl_add_u64 v[114:115], v[114:115], 1, s[6:7]
	s_waitcnt vmcnt(1)
	v_pk_add_f32 v[112:113], v[112:113], v[122:123]
	v_pk_add_f32 v[110:111], v[110:111], v[120:121]
	s_waitcnt vmcnt(0)
	v_pk_add_f32 v[108:109], v[108:109], v[126:127]
	v_pk_add_f32 v[106:107], v[106:107], v[124:125]
	global_store_dwordx4 v[116:117], v[110:113], off
	global_store_dwordx4 v[116:117], v[106:109], off offset:16
	s_cbranch_vccnz .LBB0_1288
	v_mov_b32_e32 v120, v234
	v_mov_b32_e32 v121, v235
	v_mov_b32_e32 v122, v236
	v_mov_b32_e32 v123, v237
	v_mov_b32_e32 v124, v230
	v_mov_b32_e32 v125, v231
	v_mov_b32_e32 v126, v232
	v_mov_b32_e32 v127, v233
	v_pk_mul_f32 v[128:129], v[108:109], v[122:123]
	v_pk_mul_f32 v[124:125], v[110:111], v[124:125]
	v_pk_mul_f32 v[110:111], v[110:111], v[110:111]
	v_pk_mul_f32 v[126:127], v[112:113], v[126:127]
	v_pk_mul_f32 v[112:113], v[112:113], v[112:113]
	v_add_f32_e32 v110, v110, v111
	v_add_f32_e32 v110, v112, v110
	v_pk_mul_f32 v[122:123], v[106:107], v[120:121]
	v_pk_mul_f32 v[106:107], v[106:107], v[106:107]
	v_add_f32_e32 v110, v113, v110
	v_add_f32_e32 v106, v106, v110
	v_pk_mul_f32 v[108:109], v[108:109], v[108:109]
	v_add_f32_e32 v106, v107, v106
	v_add_f32_e32 v106, v108, v106
	v_add_f32_e32 v106, v109, v106
	v_cvt_pk_bf16_f32 v120, v124, v125
	v_cvt_pk_bf16_f32 v121, v126, v127
	v_cvt_pk_bf16_f32 v122, v122, v123
	v_cvt_pk_bf16_f32 v123, v128, v129
	global_store_dwordx4 v[114:115], v[120:123], off
	s_branch .LBB0_1289

.LBB0_1289:
	global_load_dwordx4 v[108:111], v[118:119], off offset:512
	s_nop 0
	global_load_dwordx4 v[118:121], v[118:119], off offset:528
	s_and_b64 vcc, exec, s[92:93]
	s_waitcnt vmcnt(1)
	v_pk_add_f32 v[104:105], v[104:105], v[110:111]
	v_pk_add_f32 v[102:103], v[102:103], v[108:109]
	s_waitcnt vmcnt(0)
	v_pk_add_f32 v[100:101], v[100:101], v[120:121]
	v_pk_add_f32 v[98:99], v[98:99], v[118:119]
	global_store_dwordx4 v[116:117], v[102:105], off offset:512
	global_store_dwordx4 v[116:117], v[98:101], off offset:528
	s_cbranch_vccnz .LBB0_1293
	v_mov_b32_e32 v108, v242
	v_mov_b32_e32 v109, v243
	v_mov_b32_e32 v110, v244
	v_mov_b32_e32 v111, v245
	v_mov_b32_e32 v116, v238
	v_mov_b32_e32 v117, v239
	v_mov_b32_e32 v118, v240
	v_mov_b32_e32 v119, v241
	v_pk_mul_f32 v[116:117], v[102:103], v[116:117]
	v_mul_f32_e32 v103, v103, v103
	v_fmac_f32_e32 v103, v102, v102
	v_fmac_f32_e32 v103, v104, v104
	v_fmac_f32_e32 v103, v105, v105
	v_fmac_f32_e32 v103, v98, v98
	v_fmac_f32_e32 v103, v99, v99
	v_pk_mul_f32 v[112:113], v[104:105], v[118:119]
	v_pk_mul_f32 v[118:119], v[100:101], v[110:111]
	v_fmac_f32_e32 v103, v100, v100
	v_and_b32_e32 v100, 64, v200
	v_pk_mul_f32 v[110:111], v[98:99], v[108:109]
	v_xor_b32_e32 v99, 16, v200
	v_add_u32_e32 v100, 64, v100
	v_cmp_lt_i32_e32 vcc, v99, v100
	v_fmac_f32_e32 v103, v101, v101
	v_add_f32_e32 v98, v106, v103
	v_cndmask_b32_e32 v99, v200, v99, vcc
	v_lshlrev_b32_e32 v99, 2, v99
	ds_bpermute_b32 v99, v99, v98
	v_cvt_pk_bf16_f32 v108, v116, v117
	v_cvt_pk_bf16_f32 v109, v112, v113
	v_cvt_pk_bf16_f32 v110, v110, v111
	v_cvt_pk_bf16_f32 v111, v118, v119
	s_waitcnt lgkmcnt(0)
	v_add_f32_e32 v98, v98, v99
	v_xor_b32_e32 v99, 32, v200
	v_cmp_lt_i32_e32 vcc, v99, v100
	global_store_dwordx4 v[114:115], v[108:111], off offset:256
	s_nop 0
	v_cndmask_b32_e32 v99, v200, v99, vcc
	v_lshlrev_b32_e32 v99, 2, v99
	ds_bpermute_b32 v99, v99, v98
	s_and_saveexec_b64 s[22:23], s[90:91]
	s_cbranch_execz .LBB0_1292
	v_lshl_add_u64 v[100:101], v[140:141], 2, s[8:9]
	s_waitcnt lgkmcnt(0)
	v_add_f32_e32 v98, v98, v99
	global_atomic_add_f32 v[100:101], v98, off offset:64

.LBB0_1293:
	s_nop 0
	v_or_b32_e32 v98, 32, v140
	s_waitcnt lgkmcnt(0)
	v_ashrrev_i32_e32 v99, 31, v98
	v_lshlrev_b64 v[98:99], 11, v[98:99]
	v_lshl_add_u64 v[98:99], v[98:99], 0, v[146:147]
	v_lshlrev_b64 v[100:101], 2, v[98:99]
	v_lshl_add_u64 v[102:103], s[0:1], 0, v[100:101]
	global_load_dwordx4 v[104:107], v[102:103], off
	global_load_dwordx4 v[108:111], v[102:103], off offset:16
	s_and_b64 vcc, exec, s[92:93]
	v_lshl_add_u64 v[100:101], s[10:11], 0, v[100:101]
	v_lshl_add_u64 v[98:99], v[98:99], 1, s[6:7]
	s_waitcnt vmcnt(1)
	v_pk_add_f32 v[96:97], v[96:97], v[106:107]
	v_pk_add_f32 v[94:95], v[94:95], v[104:105]
	s_waitcnt vmcnt(0)
	v_pk_add_f32 v[92:93], v[92:93], v[110:111]
	v_pk_add_f32 v[90:91], v[90:91], v[108:109]
	global_store_dwordx4 v[100:101], v[94:97], off
	global_store_dwordx4 v[100:101], v[90:93], off offset:16
	s_cbranch_vccnz .LBB0_1295
	v_mov_b32_e32 v104, v234
	v_mov_b32_e32 v105, v235
	v_mov_b32_e32 v106, v236
	v_mov_b32_e32 v107, v237
	v_mov_b32_e32 v108, v230
	v_mov_b32_e32 v109, v231
	v_mov_b32_e32 v110, v232
	v_mov_b32_e32 v111, v233
	v_pk_mul_f32 v[112:113], v[92:93], v[106:107]
	v_pk_mul_f32 v[108:109], v[94:95], v[108:109]
	v_pk_mul_f32 v[94:95], v[94:95], v[94:95]
	v_pk_mul_f32 v[110:111], v[96:97], v[110:111]
	v_pk_mul_f32 v[96:97], v[96:97], v[96:97]
	v_add_f32_e32 v94, v94, v95
	v_add_f32_e32 v94, v96, v94
	v_pk_mul_f32 v[106:107], v[90:91], v[104:105]
	v_pk_mul_f32 v[90:91], v[90:91], v[90:91]
	v_add_f32_e32 v94, v97, v94
	v_add_f32_e32 v90, v90, v94
	v_pk_mul_f32 v[92:93], v[92:93], v[92:93]
	v_add_f32_e32 v90, v91, v90
	v_add_f32_e32 v90, v92, v90
	v_add_f32_e32 v90, v93, v90
	v_cvt_pk_bf16_f32 v104, v108, v109
	v_cvt_pk_bf16_f32 v105, v110, v111
	v_cvt_pk_bf16_f32 v106, v106, v107
	v_cvt_pk_bf16_f32 v107, v112, v113
	global_store_dwordx4 v[98:99], v[104:107], off
	s_branch .LBB0_1296

.LBB0_1296:
	global_load_dwordx4 v[92:95], v[102:103], off offset:512
	s_nop 0
	global_load_dwordx4 v[102:105], v[102:103], off offset:528
	s_and_b64 vcc, exec, s[92:93]
	s_waitcnt vmcnt(1)
	v_pk_add_f32 v[88:89], v[88:89], v[94:95]
	v_pk_add_f32 v[86:87], v[86:87], v[92:93]
	s_waitcnt vmcnt(0)
	v_pk_add_f32 v[84:85], v[84:85], v[104:105]
	v_pk_add_f32 v[82:83], v[82:83], v[102:103]
	global_store_dwordx4 v[100:101], v[86:89], off offset:512
	global_store_dwordx4 v[100:101], v[82:85], off offset:528
	s_cbranch_vccnz .LBB0_1300
	v_mov_b32_e32 v92, v242
	v_mov_b32_e32 v93, v243
	v_mov_b32_e32 v94, v244
	v_mov_b32_e32 v95, v245
	v_mov_b32_e32 v100, v238
	v_mov_b32_e32 v101, v239
	v_mov_b32_e32 v102, v240
	v_mov_b32_e32 v103, v241
	v_pk_mul_f32 v[100:101], v[86:87], v[100:101]
	v_mul_f32_e32 v87, v87, v87
	v_fmac_f32_e32 v87, v86, v86
	v_fmac_f32_e32 v87, v88, v88
	v_fmac_f32_e32 v87, v89, v89
	v_fmac_f32_e32 v87, v82, v82
	v_fmac_f32_e32 v87, v83, v83
	v_pk_mul_f32 v[96:97], v[88:89], v[102:103]
	v_pk_mul_f32 v[102:103], v[84:85], v[94:95]
	v_fmac_f32_e32 v87, v84, v84
	v_and_b32_e32 v84, 64, v200
	v_pk_mul_f32 v[94:95], v[82:83], v[92:93]
	v_xor_b32_e32 v83, 16, v200
	v_add_u32_e32 v84, 64, v84
	v_cmp_lt_i32_e32 vcc, v83, v84
	v_fmac_f32_e32 v87, v85, v85
	v_add_f32_e32 v82, v90, v87
	v_cndmask_b32_e32 v83, v200, v83, vcc
	v_lshlrev_b32_e32 v83, 2, v83
	ds_bpermute_b32 v83, v83, v82
	v_cvt_pk_bf16_f32 v92, v100, v101
	v_cvt_pk_bf16_f32 v93, v96, v97
	v_cvt_pk_bf16_f32 v94, v94, v95
	v_cvt_pk_bf16_f32 v95, v102, v103
	s_waitcnt lgkmcnt(0)
	v_add_f32_e32 v82, v82, v83
	v_xor_b32_e32 v83, 32, v200
	v_cmp_lt_i32_e32 vcc, v83, v84
	global_store_dwordx4 v[98:99], v[92:95], off offset:256
	s_nop 0
	v_cndmask_b32_e32 v83, v200, v83, vcc
	v_lshlrev_b32_e32 v83, 2, v83
	ds_bpermute_b32 v83, v83, v82
	s_and_saveexec_b64 s[22:23], s[90:91]
	s_cbranch_execz .LBB0_1299
	v_lshl_add_u64 v[84:85], v[140:141], 2, s[8:9]
	s_waitcnt lgkmcnt(0)
	v_add_f32_e32 v82, v82, v83
	global_atomic_add_f32 v[84:85], v82, off offset:128

.LBB0_1300:
	s_nop 0
	v_or_b32_e32 v82, 48, v140
	s_waitcnt lgkmcnt(0)
	v_ashrrev_i32_e32 v83, 31, v82
	v_lshlrev_b64 v[82:83], 11, v[82:83]
	v_lshl_add_u64 v[82:83], v[82:83], 0, v[146:147]
	v_lshlrev_b64 v[84:85], 2, v[82:83]
	v_lshl_add_u64 v[86:87], s[0:1], 0, v[84:85]
	global_load_dwordx4 v[88:91], v[86:87], off
	global_load_dwordx4 v[92:95], v[86:87], off offset:16
	s_and_b64 vcc, exec, s[92:93]
	v_lshl_add_u64 v[84:85], s[10:11], 0, v[84:85]
	v_lshl_add_u64 v[82:83], v[82:83], 1, s[6:7]
	s_waitcnt vmcnt(1)
	v_pk_add_f32 v[80:81], v[80:81], v[90:91]
	v_pk_add_f32 v[78:79], v[78:79], v[88:89]
	s_waitcnt vmcnt(0)
	v_pk_add_f32 v[76:77], v[76:77], v[94:95]
	v_pk_add_f32 v[74:75], v[74:75], v[92:93]
	global_store_dwordx4 v[84:85], v[78:81], off
	global_store_dwordx4 v[84:85], v[74:77], off offset:16
	s_cbranch_vccnz .LBB0_1302
	v_mov_b32_e32 v88, v234
	v_mov_b32_e32 v89, v235
	v_mov_b32_e32 v90, v236
	v_mov_b32_e32 v91, v237
	v_mov_b32_e32 v92, v230
	v_mov_b32_e32 v93, v231
	v_mov_b32_e32 v94, v232
	v_mov_b32_e32 v95, v233
	v_pk_mul_f32 v[96:97], v[76:77], v[90:91]
	v_pk_mul_f32 v[92:93], v[78:79], v[92:93]
	v_pk_mul_f32 v[78:79], v[78:79], v[78:79]
	v_pk_mul_f32 v[94:95], v[80:81], v[94:95]
	v_pk_mul_f32 v[80:81], v[80:81], v[80:81]
	v_add_f32_e32 v78, v78, v79
	v_add_f32_e32 v78, v80, v78
	v_pk_mul_f32 v[90:91], v[74:75], v[88:89]
	v_pk_mul_f32 v[74:75], v[74:75], v[74:75]
	v_add_f32_e32 v78, v81, v78
	v_add_f32_e32 v74, v74, v78
	v_pk_mul_f32 v[76:77], v[76:77], v[76:77]
	v_add_f32_e32 v74, v75, v74
	v_add_f32_e32 v74, v76, v74
	v_add_f32_e32 v74, v77, v74
	v_cvt_pk_bf16_f32 v88, v92, v93
	v_cvt_pk_bf16_f32 v89, v94, v95
	v_cvt_pk_bf16_f32 v90, v90, v91
	v_cvt_pk_bf16_f32 v91, v96, v97
	global_store_dwordx4 v[82:83], v[88:91], off
	s_branch .LBB0_1303

.LBB0_1303:
	global_load_dwordx4 v[76:79], v[86:87], off offset:512
	s_nop 0
	global_load_dwordx4 v[86:89], v[86:87], off offset:528
	s_and_b64 vcc, exec, s[92:93]
	s_waitcnt vmcnt(1)
	v_pk_add_f32 v[72:73], v[72:73], v[78:79]
	v_pk_add_f32 v[70:71], v[70:71], v[76:77]
	s_waitcnt vmcnt(0)
	v_pk_add_f32 v[68:69], v[68:69], v[88:89]
	v_pk_add_f32 v[66:67], v[66:67], v[86:87]
	global_store_dwordx4 v[84:85], v[70:73], off offset:512
	global_store_dwordx4 v[84:85], v[66:69], off offset:528
	s_cbranch_vccnz .LBB0_1307
	v_mov_b32_e32 v76, v242
	v_mov_b32_e32 v77, v243
	v_mov_b32_e32 v78, v244
	v_mov_b32_e32 v79, v245
	v_mov_b32_e32 v84, v238
	v_mov_b32_e32 v85, v239
	v_mov_b32_e32 v86, v240
	v_mov_b32_e32 v87, v241
	v_pk_mul_f32 v[84:85], v[70:71], v[84:85]
	v_mul_f32_e32 v71, v71, v71
	v_fmac_f32_e32 v71, v70, v70
	v_fmac_f32_e32 v71, v72, v72
	v_fmac_f32_e32 v71, v73, v73
	v_fmac_f32_e32 v71, v66, v66
	v_fmac_f32_e32 v71, v67, v67
	v_pk_mul_f32 v[80:81], v[72:73], v[86:87]
	v_pk_mul_f32 v[86:87], v[68:69], v[78:79]
	v_fmac_f32_e32 v71, v68, v68
	v_and_b32_e32 v68, 64, v200
	v_pk_mul_f32 v[78:79], v[66:67], v[76:77]
	v_xor_b32_e32 v67, 16, v200
	v_add_u32_e32 v68, 64, v68
	v_cmp_lt_i32_e32 vcc, v67, v68
	v_fmac_f32_e32 v71, v69, v69
	v_add_f32_e32 v66, v74, v71
	v_cndmask_b32_e32 v67, v200, v67, vcc
	v_lshlrev_b32_e32 v67, 2, v67
	ds_bpermute_b32 v67, v67, v66
	v_cvt_pk_bf16_f32 v76, v84, v85
	v_cvt_pk_bf16_f32 v77, v80, v81
	v_cvt_pk_bf16_f32 v78, v78, v79
	v_cvt_pk_bf16_f32 v79, v86, v87
	s_waitcnt lgkmcnt(0)
	v_add_f32_e32 v66, v66, v67
	v_xor_b32_e32 v67, 32, v200
	v_cmp_lt_i32_e32 vcc, v67, v68
	global_store_dwordx4 v[82:83], v[76:79], off offset:256
	s_nop 0
	v_cndmask_b32_e32 v67, v200, v67, vcc
	v_lshlrev_b32_e32 v67, 2, v67
	ds_bpermute_b32 v67, v67, v66
	s_and_saveexec_b64 s[22:23], s[90:91]
	s_cbranch_execz .LBB0_1306
	v_lshl_add_u64 v[68:69], v[140:141], 2, s[8:9]
	s_waitcnt lgkmcnt(0)
	v_add_f32_e32 v66, v66, v67
	global_atomic_add_f32 v[68:69], v66, off offset:192

.LBB0_1307:
	s_mov_b64 s[22:23], 0x40000
	s_waitcnt lgkmcnt(0)
	v_lshl_add_u64 v[66:67], v[144:145], 0, s[22:23]
	v_lshlrev_b64 v[68:69], 2, v[66:67]
	v_lshl_add_u64 v[70:71], s[0:1], 0, v[68:69]
	global_load_dwordx4 v[72:75], v[70:71], off
	global_load_dwordx4 v[76:79], v[70:71], off offset:16
	s_and_b64 vcc, exec, s[92:93]
	v_lshl_add_u64 v[68:69], s[10:11], 0, v[68:69]
	v_lshl_add_u64 v[66:67], v[66:67], 1, s[6:7]
	s_waitcnt vmcnt(1)
	v_pk_add_f32 v[64:65], v[64:65], v[74:75]
	v_pk_add_f32 v[62:63], v[62:63], v[72:73]
	s_waitcnt vmcnt(0)
	v_pk_add_f32 v[60:61], v[60:61], v[78:79]
	v_pk_add_f32 v[58:59], v[58:59], v[76:77]
	global_store_dwordx4 v[68:69], v[62:65], off
	global_store_dwordx4 v[68:69], v[58:61], off offset:16
	s_cbranch_vccnz .LBB0_1309
	v_mov_b32_e32 v72, v234
	v_mov_b32_e32 v73, v235
	v_mov_b32_e32 v74, v236
	v_mov_b32_e32 v75, v237
	v_mov_b32_e32 v76, v230
	v_mov_b32_e32 v77, v231
	v_mov_b32_e32 v78, v232
	v_mov_b32_e32 v79, v233
	v_pk_mul_f32 v[80:81], v[60:61], v[74:75]
	v_pk_mul_f32 v[76:77], v[62:63], v[76:77]
	v_pk_mul_f32 v[62:63], v[62:63], v[62:63]
	v_pk_mul_f32 v[78:79], v[64:65], v[78:79]
	v_pk_mul_f32 v[64:65], v[64:65], v[64:65]
	v_add_f32_e32 v62, v62, v63
	v_add_f32_e32 v62, v64, v62
	v_pk_mul_f32 v[74:75], v[58:59], v[72:73]
	v_pk_mul_f32 v[58:59], v[58:59], v[58:59]
	v_add_f32_e32 v62, v65, v62
	v_add_f32_e32 v58, v58, v62
	v_pk_mul_f32 v[60:61], v[60:61], v[60:61]
	v_add_f32_e32 v58, v59, v58
	v_add_f32_e32 v58, v60, v58
	v_add_f32_e32 v58, v61, v58
	v_cvt_pk_bf16_f32 v72, v76, v77
	v_cvt_pk_bf16_f32 v73, v78, v79
	v_cvt_pk_bf16_f32 v74, v74, v75
	v_cvt_pk_bf16_f32 v75, v80, v81
	global_store_dwordx4 v[66:67], v[72:75], off
	s_branch .LBB0_1310

.LBB0_1310:
	global_load_dwordx4 v[60:63], v[70:71], off offset:512
	s_nop 0
	global_load_dwordx4 v[70:73], v[70:71], off offset:528
	s_and_b64 vcc, exec, s[92:93]
	s_waitcnt vmcnt(1)
	v_pk_add_f32 v[56:57], v[56:57], v[62:63]
	v_pk_add_f32 v[54:55], v[54:55], v[60:61]
	s_waitcnt vmcnt(0)
	v_pk_add_f32 v[52:53], v[52:53], v[72:73]
	v_pk_add_f32 v[50:51], v[50:51], v[70:71]
	global_store_dwordx4 v[68:69], v[54:57], off offset:512
	global_store_dwordx4 v[68:69], v[50:53], off offset:528
	s_cbranch_vccnz .LBB0_1314
	v_mov_b32_e32 v60, v242
	v_mov_b32_e32 v61, v243
	v_mov_b32_e32 v62, v244
	v_mov_b32_e32 v63, v245
	v_mov_b32_e32 v68, v238
	v_mov_b32_e32 v69, v239
	v_mov_b32_e32 v70, v240
	v_mov_b32_e32 v71, v241
	v_pk_mul_f32 v[68:69], v[54:55], v[68:69]
	v_mul_f32_e32 v55, v55, v55
	v_fmac_f32_e32 v55, v54, v54
	v_fmac_f32_e32 v55, v56, v56
	v_fmac_f32_e32 v55, v57, v57
	v_fmac_f32_e32 v55, v50, v50
	v_fmac_f32_e32 v55, v51, v51
	v_pk_mul_f32 v[64:65], v[56:57], v[70:71]
	v_pk_mul_f32 v[70:71], v[52:53], v[62:63]
	v_fmac_f32_e32 v55, v52, v52
	v_and_b32_e32 v52, 64, v200
	v_pk_mul_f32 v[62:63], v[50:51], v[60:61]
	v_xor_b32_e32 v51, 16, v200
	v_add_u32_e32 v52, 64, v52
	v_cmp_lt_i32_e32 vcc, v51, v52
	v_fmac_f32_e32 v55, v53, v53
	v_add_f32_e32 v50, v58, v55
	v_cndmask_b32_e32 v51, v200, v51, vcc
	v_lshlrev_b32_e32 v51, 2, v51
	ds_bpermute_b32 v51, v51, v50
	v_cvt_pk_bf16_f32 v60, v68, v69
	v_cvt_pk_bf16_f32 v61, v64, v65
	v_cvt_pk_bf16_f32 v62, v62, v63
	v_cvt_pk_bf16_f32 v63, v70, v71
	s_waitcnt lgkmcnt(0)
	v_add_f32_e32 v50, v50, v51
	v_xor_b32_e32 v51, 32, v200
	v_cmp_lt_i32_e32 vcc, v51, v52
	global_store_dwordx4 v[66:67], v[60:63], off offset:256
	s_nop 0
	v_cndmask_b32_e32 v51, v200, v51, vcc
	v_lshlrev_b32_e32 v51, 2, v51
	ds_bpermute_b32 v51, v51, v50
	s_and_saveexec_b64 s[22:23], s[90:91]
	s_cbranch_execz .LBB0_1313
	v_lshl_add_u64 v[52:53], v[140:141], 2, s[8:9]
	s_waitcnt lgkmcnt(0)
	v_add_f32_e32 v50, v50, v51
	global_atomic_add_f32 v[52:53], v50, off offset:512

.LBB0_1314:
	s_mov_b64 s[22:23], 0x48000
	s_waitcnt lgkmcnt(0)
	v_lshl_add_u64 v[50:51], v[144:145], 0, s[22:23]
	v_lshlrev_b64 v[52:53], 2, v[50:51]
	v_lshl_add_u64 v[54:55], s[0:1], 0, v[52:53]
	global_load_dwordx4 v[56:59], v[54:55], off
	global_load_dwordx4 v[60:63], v[54:55], off offset:16
	s_and_b64 vcc, exec, s[92:93]
	v_lshl_add_u64 v[52:53], s[10:11], 0, v[52:53]
	v_lshl_add_u64 v[50:51], v[50:51], 1, s[6:7]
	s_waitcnt vmcnt(1)
	v_pk_add_f32 v[48:49], v[48:49], v[58:59]
	v_pk_add_f32 v[46:47], v[46:47], v[56:57]
	s_waitcnt vmcnt(0)
	v_pk_add_f32 v[44:45], v[44:45], v[62:63]
	v_pk_add_f32 v[42:43], v[42:43], v[60:61]
	global_store_dwordx4 v[52:53], v[46:49], off
	global_store_dwordx4 v[52:53], v[42:45], off offset:16
	s_cbranch_vccnz .LBB0_1316
	v_mov_b32_e32 v56, v234
	v_mov_b32_e32 v57, v235
	v_mov_b32_e32 v58, v236
	v_mov_b32_e32 v59, v237
	v_mov_b32_e32 v60, v230
	v_mov_b32_e32 v61, v231
	v_mov_b32_e32 v62, v232
	v_mov_b32_e32 v63, v233
	v_pk_mul_f32 v[64:65], v[44:45], v[58:59]
	v_pk_mul_f32 v[60:61], v[46:47], v[60:61]
	v_pk_mul_f32 v[46:47], v[46:47], v[46:47]
	v_pk_mul_f32 v[62:63], v[48:49], v[62:63]
	v_pk_mul_f32 v[48:49], v[48:49], v[48:49]
	v_add_f32_e32 v46, v46, v47
	v_add_f32_e32 v46, v48, v46
	v_pk_mul_f32 v[58:59], v[42:43], v[56:57]
	v_pk_mul_f32 v[42:43], v[42:43], v[42:43]
	v_add_f32_e32 v46, v49, v46
	v_add_f32_e32 v42, v42, v46
	v_pk_mul_f32 v[44:45], v[44:45], v[44:45]
	v_add_f32_e32 v42, v43, v42
	v_add_f32_e32 v42, v44, v42
	v_add_f32_e32 v42, v45, v42
	v_cvt_pk_bf16_f32 v56, v60, v61
	v_cvt_pk_bf16_f32 v57, v62, v63
	v_cvt_pk_bf16_f32 v58, v58, v59
	v_cvt_pk_bf16_f32 v59, v64, v65
	global_store_dwordx4 v[50:51], v[56:59], off
	s_branch .LBB0_1317

.LBB0_1317:
	global_load_dwordx4 v[44:47], v[54:55], off offset:512
	s_nop 0
	global_load_dwordx4 v[54:57], v[54:55], off offset:528
	s_and_b64 vcc, exec, s[92:93]
	s_waitcnt vmcnt(1)
	v_pk_add_f32 v[40:41], v[40:41], v[46:47]
	v_pk_add_f32 v[38:39], v[38:39], v[44:45]
	s_waitcnt vmcnt(0)
	v_pk_add_f32 v[36:37], v[36:37], v[56:57]
	v_pk_add_f32 v[34:35], v[34:35], v[54:55]
	global_store_dwordx4 v[52:53], v[38:41], off offset:512
	global_store_dwordx4 v[52:53], v[34:37], off offset:528
	s_cbranch_vccnz .LBB0_1321
	v_mov_b32_e32 v44, v242
	v_mov_b32_e32 v45, v243
	v_mov_b32_e32 v46, v244
	v_mov_b32_e32 v47, v245
	v_mov_b32_e32 v52, v238
	v_mov_b32_e32 v53, v239
	v_mov_b32_e32 v54, v240
	v_mov_b32_e32 v55, v241
	v_pk_mul_f32 v[52:53], v[38:39], v[52:53]
	v_mul_f32_e32 v39, v39, v39
	v_fmac_f32_e32 v39, v38, v38
	v_fmac_f32_e32 v39, v40, v40
	v_fmac_f32_e32 v39, v41, v41
	v_fmac_f32_e32 v39, v34, v34
	v_fmac_f32_e32 v39, v35, v35
	v_pk_mul_f32 v[48:49], v[40:41], v[54:55]
	v_pk_mul_f32 v[54:55], v[36:37], v[46:47]
	v_fmac_f32_e32 v39, v36, v36
	v_and_b32_e32 v36, 64, v200
	v_pk_mul_f32 v[46:47], v[34:35], v[44:45]
	v_xor_b32_e32 v35, 16, v200
	v_add_u32_e32 v36, 64, v36
	v_cmp_lt_i32_e32 vcc, v35, v36
	v_fmac_f32_e32 v39, v37, v37
	v_add_f32_e32 v34, v42, v39
	v_cndmask_b32_e32 v35, v200, v35, vcc
	v_lshlrev_b32_e32 v35, 2, v35
	ds_bpermute_b32 v35, v35, v34
	v_cvt_pk_bf16_f32 v44, v52, v53
	v_cvt_pk_bf16_f32 v45, v48, v49
	v_cvt_pk_bf16_f32 v46, v46, v47
	v_cvt_pk_bf16_f32 v47, v54, v55
	s_waitcnt lgkmcnt(0)
	v_add_f32_e32 v34, v34, v35
	v_xor_b32_e32 v35, 32, v200
	v_cmp_lt_i32_e32 vcc, v35, v36
	global_store_dwordx4 v[50:51], v[44:47], off offset:256
	s_nop 0
	v_cndmask_b32_e32 v35, v200, v35, vcc
	v_lshlrev_b32_e32 v35, 2, v35
	ds_bpermute_b32 v35, v35, v34
	s_and_saveexec_b64 s[22:23], s[90:91]
	s_cbranch_execz .LBB0_1320
	v_lshl_add_u64 v[36:37], v[140:141], 2, s[8:9]
	s_waitcnt lgkmcnt(0)
	v_add_f32_e32 v34, v34, v35
	global_atomic_add_f32 v[36:37], v34, off offset:576

.LBB0_1321:
	s_mov_b64 s[22:23], 0x50000
	s_waitcnt lgkmcnt(0)
	v_lshl_add_u64 v[34:35], v[144:145], 0, s[22:23]
	v_lshlrev_b64 v[36:37], 2, v[34:35]
	v_lshl_add_u64 v[38:39], s[0:1], 0, v[36:37]
	global_load_dwordx4 v[40:43], v[38:39], off
	global_load_dwordx4 v[44:47], v[38:39], off offset:16
	s_and_b64 vcc, exec, s[92:93]
	v_lshl_add_u64 v[36:37], s[10:11], 0, v[36:37]
	v_lshl_add_u64 v[34:35], v[34:35], 1, s[6:7]
	s_waitcnt vmcnt(1)
	v_pk_add_f32 v[32:33], v[32:33], v[42:43]
	v_pk_add_f32 v[30:31], v[30:31], v[40:41]
	s_waitcnt vmcnt(0)
	v_pk_add_f32 v[28:29], v[28:29], v[46:47]
	v_pk_add_f32 v[26:27], v[26:27], v[44:45]
	global_store_dwordx4 v[36:37], v[30:33], off
	global_store_dwordx4 v[36:37], v[26:29], off offset:16
	s_cbranch_vccnz .LBB0_1323
	v_mov_b32_e32 v40, v234
	v_mov_b32_e32 v41, v235
	v_mov_b32_e32 v42, v236
	v_mov_b32_e32 v43, v237
	v_mov_b32_e32 v44, v230
	v_mov_b32_e32 v45, v231
	v_mov_b32_e32 v46, v232
	v_mov_b32_e32 v47, v233
	v_pk_mul_f32 v[48:49], v[28:29], v[42:43]
	v_pk_mul_f32 v[44:45], v[30:31], v[44:45]
	v_pk_mul_f32 v[30:31], v[30:31], v[30:31]
	v_pk_mul_f32 v[46:47], v[32:33], v[46:47]
	v_pk_mul_f32 v[32:33], v[32:33], v[32:33]
	v_add_f32_e32 v30, v30, v31
	v_add_f32_e32 v30, v32, v30
	v_pk_mul_f32 v[42:43], v[26:27], v[40:41]
	v_pk_mul_f32 v[26:27], v[26:27], v[26:27]
	v_add_f32_e32 v30, v33, v30
	v_add_f32_e32 v26, v26, v30
	v_pk_mul_f32 v[28:29], v[28:29], v[28:29]
	v_add_f32_e32 v26, v27, v26
	v_add_f32_e32 v26, v28, v26
	v_add_f32_e32 v26, v29, v26
	v_cvt_pk_bf16_f32 v40, v44, v45
	v_cvt_pk_bf16_f32 v41, v46, v47
	v_cvt_pk_bf16_f32 v42, v42, v43
	v_cvt_pk_bf16_f32 v43, v48, v49
	global_store_dwordx4 v[34:35], v[40:43], off
	s_branch .LBB0_1324

.LBB0_1324:
	global_load_dwordx4 v[28:31], v[38:39], off offset:512
	s_nop 0
	global_load_dwordx4 v[38:41], v[38:39], off offset:528
	s_and_b64 vcc, exec, s[92:93]
	s_waitcnt vmcnt(1)
	v_pk_add_f32 v[24:25], v[24:25], v[30:31]
	v_pk_add_f32 v[22:23], v[22:23], v[28:29]
	s_waitcnt vmcnt(0)
	v_pk_add_f32 v[20:21], v[20:21], v[40:41]
	v_pk_add_f32 v[18:19], v[18:19], v[38:39]
	global_store_dwordx4 v[36:37], v[22:25], off offset:512
	global_store_dwordx4 v[36:37], v[18:21], off offset:528
	s_cbranch_vccnz .LBB0_1328
	v_mov_b32_e32 v28, v242
	v_mov_b32_e32 v29, v243
	v_mov_b32_e32 v30, v244
	v_mov_b32_e32 v31, v245
	v_mov_b32_e32 v36, v238
	v_mov_b32_e32 v37, v239
	v_mov_b32_e32 v38, v240
	v_mov_b32_e32 v39, v241
	v_pk_mul_f32 v[36:37], v[22:23], v[36:37]
	v_mul_f32_e32 v23, v23, v23
	v_fmac_f32_e32 v23, v22, v22
	v_fmac_f32_e32 v23, v24, v24
	v_fmac_f32_e32 v23, v25, v25
	v_fmac_f32_e32 v23, v18, v18
	v_fmac_f32_e32 v23, v19, v19
	v_pk_mul_f32 v[32:33], v[24:25], v[38:39]
	v_pk_mul_f32 v[38:39], v[20:21], v[30:31]
	v_fmac_f32_e32 v23, v20, v20
	v_and_b32_e32 v20, 64, v200
	v_pk_mul_f32 v[30:31], v[18:19], v[28:29]
	v_xor_b32_e32 v19, 16, v200
	v_add_u32_e32 v20, 64, v20
	v_cmp_lt_i32_e32 vcc, v19, v20
	v_fmac_f32_e32 v23, v21, v21
	v_add_f32_e32 v18, v26, v23
	v_cndmask_b32_e32 v19, v200, v19, vcc
	v_lshlrev_b32_e32 v19, 2, v19
	ds_bpermute_b32 v19, v19, v18
	v_cvt_pk_bf16_f32 v28, v36, v37
	v_cvt_pk_bf16_f32 v29, v32, v33
	v_cvt_pk_bf16_f32 v30, v30, v31
	v_cvt_pk_bf16_f32 v31, v38, v39
	s_waitcnt lgkmcnt(0)
	v_add_f32_e32 v18, v18, v19
	v_xor_b32_e32 v19, 32, v200
	v_cmp_lt_i32_e32 vcc, v19, v20
	global_store_dwordx4 v[34:35], v[28:31], off offset:256
	s_nop 0
	v_cndmask_b32_e32 v19, v200, v19, vcc
	v_lshlrev_b32_e32 v19, 2, v19
	ds_bpermute_b32 v19, v19, v18
	s_and_saveexec_b64 s[22:23], s[90:91]
	s_cbranch_execz .LBB0_1327
	v_lshl_add_u64 v[20:21], v[140:141], 2, s[8:9]
	s_waitcnt lgkmcnt(0)
	v_add_f32_e32 v18, v18, v19
	global_atomic_add_f32 v[20:21], v18, off offset:640

.LBB0_1328:
	s_mov_b64 s[22:23], 0x58000
	s_waitcnt lgkmcnt(0)
	v_lshl_add_u64 v[18:19], v[144:145], 0, s[22:23]
	v_lshlrev_b64 v[20:21], 2, v[18:19]
	v_lshl_add_u64 v[22:23], s[0:1], 0, v[20:21]
	global_load_dwordx4 v[24:27], v[22:23], off
	global_load_dwordx4 v[28:31], v[22:23], off offset:16
	s_and_b64 vcc, exec, s[92:93]
	v_lshl_add_u64 v[20:21], s[10:11], 0, v[20:21]
	v_lshl_add_u64 v[18:19], v[18:19], 1, s[6:7]
	s_waitcnt vmcnt(1)
	v_pk_add_f32 v[16:17], v[16:17], v[26:27]
	v_pk_add_f32 v[14:15], v[14:15], v[24:25]
	s_waitcnt vmcnt(0)
	v_pk_add_f32 v[12:13], v[12:13], v[30:31]
	v_pk_add_f32 v[10:11], v[10:11], v[28:29]
	global_store_dwordx4 v[20:21], v[14:17], off
	global_store_dwordx4 v[20:21], v[10:13], off offset:16
	s_cbranch_vccnz .LBB0_1330
	v_mov_b32_e32 v24, v234
	v_mov_b32_e32 v25, v235
	v_mov_b32_e32 v26, v236
	v_mov_b32_e32 v27, v237
	v_mov_b32_e32 v28, v230
	v_mov_b32_e32 v29, v231
	v_mov_b32_e32 v30, v232
	v_mov_b32_e32 v31, v233
	v_pk_mul_f32 v[32:33], v[12:13], v[26:27]
	v_pk_mul_f32 v[28:29], v[14:15], v[28:29]
	v_pk_mul_f32 v[14:15], v[14:15], v[14:15]
	v_pk_mul_f32 v[30:31], v[16:17], v[30:31]
	v_pk_mul_f32 v[16:17], v[16:17], v[16:17]
	v_add_f32_e32 v14, v14, v15
	v_add_f32_e32 v14, v16, v14
	v_pk_mul_f32 v[26:27], v[10:11], v[24:25]
	v_pk_mul_f32 v[10:11], v[10:11], v[10:11]
	v_add_f32_e32 v14, v17, v14
	v_add_f32_e32 v10, v10, v14
	v_pk_mul_f32 v[12:13], v[12:13], v[12:13]
	v_add_f32_e32 v10, v11, v10
	v_add_f32_e32 v10, v12, v10
	v_add_f32_e32 v10, v13, v10
	v_cvt_pk_bf16_f32 v24, v28, v29
	v_cvt_pk_bf16_f32 v25, v30, v31
	v_cvt_pk_bf16_f32 v26, v26, v27
	v_cvt_pk_bf16_f32 v27, v32, v33
	global_store_dwordx4 v[18:19], v[24:27], off
	s_branch .LBB0_1331

.LBB0_1331:
	global_load_dwordx4 v[12:15], v[22:23], off offset:512
	s_nop 0
	global_load_dwordx4 v[22:25], v[22:23], off offset:528
	s_and_b64 vcc, exec, s[92:93]
	s_waitcnt vmcnt(1)
	v_pk_add_f32 v[8:9], v[8:9], v[14:15]
	v_pk_add_f32 v[6:7], v[6:7], v[12:13]
	s_waitcnt vmcnt(0)
	v_pk_add_f32 v[4:5], v[4:5], v[24:25]
	v_pk_add_f32 v[2:3], v[2:3], v[22:23]
	global_store_dwordx4 v[20:21], v[6:9], off offset:512
	global_store_dwordx4 v[20:21], v[2:5], off offset:528
	s_cbranch_vccnz .LBB0_1335
	v_mov_b32_e32 v12, v242
	v_mov_b32_e32 v13, v243
	v_mov_b32_e32 v14, v244
	v_mov_b32_e32 v15, v245
	v_mov_b32_e32 v20, v238
	v_mov_b32_e32 v21, v239
	v_mov_b32_e32 v22, v240
	v_mov_b32_e32 v23, v241
	v_pk_mul_f32 v[20:21], v[6:7], v[20:21]
	v_mul_f32_e32 v7, v7, v7
	v_fmac_f32_e32 v7, v6, v6
	v_fmac_f32_e32 v7, v8, v8
	v_fmac_f32_e32 v7, v9, v9
	v_fmac_f32_e32 v7, v2, v2
	v_fmac_f32_e32 v7, v3, v3
	v_pk_mul_f32 v[16:17], v[8:9], v[22:23]
	v_pk_mul_f32 v[22:23], v[4:5], v[14:15]
	v_fmac_f32_e32 v7, v4, v4
	v_and_b32_e32 v4, 64, v200
	v_pk_mul_f32 v[14:15], v[2:3], v[12:13]
	v_xor_b32_e32 v3, 16, v200
	v_add_u32_e32 v4, 64, v4
	v_cmp_lt_i32_e32 vcc, v3, v4
	v_fmac_f32_e32 v7, v5, v5
	v_add_f32_e32 v2, v10, v7
	v_cndmask_b32_e32 v3, v200, v3, vcc
	v_lshlrev_b32_e32 v3, 2, v3
	ds_bpermute_b32 v3, v3, v2
	v_cvt_pk_bf16_f32 v12, v20, v21
	v_cvt_pk_bf16_f32 v13, v16, v17
	v_cvt_pk_bf16_f32 v14, v14, v15
	v_cvt_pk_bf16_f32 v15, v22, v23
	s_waitcnt lgkmcnt(0)
	v_add_f32_e32 v2, v2, v3
	v_xor_b32_e32 v3, 32, v200
	v_cmp_lt_i32_e32 vcc, v3, v4
	global_store_dwordx4 v[18:19], v[12:15], off offset:256
	s_nop 0
	v_cndmask_b32_e32 v3, v200, v3, vcc
	v_lshlrev_b32_e32 v3, 2, v3
	ds_bpermute_b32 v3, v3, v2
	s_and_saveexec_b64 s[22:23], s[90:91]
	s_cbranch_execz .LBB0_1334
	v_lshl_add_u64 v[4:5], v[140:141], 2, s[8:9]
	s_waitcnt lgkmcnt(0)
	v_add_f32_e32 v2, v2, v3
	global_atomic_add_f32 v[4:5], v2, off offset:704
